# all validated edits combined (A trims, scalar bias adds, scalar norm math, B/C/D max-tree trims, vmcnt cleanup, no-swap P packing)
# speedup vs baseline: 1.0085x; 1.0070x over previous
; __device__ __forceinline__ void qkt12_roll(f32x16& p0, f32x16& p1, const f32x16& negm, int kb, int qa, const bf16x8* qr) {
;   const int a0 = kb ^ (0 << 5); const bf16x8 x0 = lds_rd128<0>(a0), y0 = lds_rd128<12288>(a0);
;   const int a1 = kb ^ (1 << 5); const bf16x8 x1 = lds_rd128<0>(a1), y1 = lds_rd128<12288>(a1);
;   asm volatile("s_waitcnt lgkmcnt(2)" ::: "memory"); SBAR();
;   p0 = __builtin_amdgcn_mfma_f32_32x32x16_bf16(x0, qr[0], negm, 0, 0, 0); p1 = __builtin_amdgcn_mfma_f32_32x32x16_bf16(y0, qr[0], negm, 0, 0, 0);
;   const int a2 = kb ^ (2 << 5); const bf16x8 x2 = lds_rd128<0>(a2), y2 = lds_rd128<12288>(a2);
;   asm volatile("s_waitcnt lgkmcnt(2)" ::: "memory"); SBAR();
;   p0 = __builtin_amdgcn_mfma_f32_32x32x16_bf16(x1, qr[1], p0, 0, 0, 0); p1 = __builtin_amdgcn_mfma_f32_32x32x16_bf16(y1, qr[1], p1, 0, 0, 0);
;   const int a3 = kb ^ (3 << 5); const bf16x8 x3 = lds_rd128<0>(a3), y3 = lds_rd128<12288>(a3);
;   asm volatile("s_waitcnt lgkmcnt(2)" ::: "memory"); SBAR();
;   p0 = __builtin_amdgcn_mfma_f32_32x32x16_bf16(x2, qr[2], p0, 0, 0, 0); p1 = __builtin_amdgcn_mfma_f32_32x32x16_bf16(y2, qr[2], p1, 0, 0, 0);
;   const int a4 = kb ^ (0 << 5); const bf16x8 x4 = lds_rd128<128>(a4), y4 = lds_rd128<12416>(a4);
;   asm volatile("s_waitcnt lgkmcnt(2)" ::: "memory"); SBAR();
;   p0 = __builtin_amdgcn_mfma_f32_32x32x16_bf16(x3, qr[3], p0, 0, 0, 0); p1 = __builtin_amdgcn_mfma_f32_32x32x16_bf16(y3, qr[3], p1, 0, 0, 0);
;   const int a5 = kb ^ (1 << 5); const bf16x8 x5 = lds_rd128<128>(a5), y5 = lds_rd128<12416>(a5);
;   asm volatile("s_waitcnt lgkmcnt(2)" ::: "memory"); SBAR();
;   p0 = __builtin_amdgcn_mfma_f32_32x32x16_bf16(x4, qr[4], p0, 0, 0, 0); p1 = __builtin_amdgcn_mfma_f32_32x32x16_bf16(y4, qr[4], p1, 0, 0, 0);
;   const int a6 = kb ^ (2 << 5); const bf16x8 x6 = lds_rd128<128>(a6), y6 = lds_rd128<12416>(a6);
;   asm volatile("s_waitcnt lgkmcnt(2)" ::: "memory"); SBAR();
;   p0 = __builtin_amdgcn_mfma_f32_32x32x16_bf16(x5, qr[5], p0, 0, 0, 0); p1 = __builtin_amdgcn_mfma_f32_32x32x16_bf16(y5, qr[5], p1, 0, 0, 0);
;   const int a7 = kb ^ (3 << 5); const bf16x8 x7 = lds_rd128<128>(a7), y7 = lds_rd128<12416>(a7);
;   asm volatile("s_waitcnt lgkmcnt(2)" ::: "memory"); SBAR();
;   p0 = __builtin_amdgcn_mfma_f32_32x32x16_bf16(x6, qr[6], p0, 0, 0, 0); p1 = __builtin_amdgcn_mfma_f32_32x32x16_bf16(y6, qr[6], p1, 0, 0, 0);
.LBB0_360:
	v_exp_f32_e32 v66, v66
	v_exp_f32_e32 v67, v67
	v_exp_f32_e32 v68, v68
	v_exp_f32_e32 v69, v69
	v_exp_f32_e32 v70, v70
	v_exp_f32_e32 v71, v71
	v_exp_f32_e32 v72, v72
	v_exp_f32_e32 v73, v73
	v_add_f32_e32 v98, v148, v146
	v_add_f32_e32 v99, v159, v161
	v_add_f32_e32 v100, v149, v147
	v_add_f32_e32 v101, v158, v160
	v_exp_f32_e32 v74, v74
	v_exp_f32_e32 v75, v75
	v_exp_f32_e32 v76, v76
	v_exp_f32_e32 v77, v77
	v_add_f32_e32 v98, v150, v98
	v_add_f32_e32 v99, v157, v99
	v_add_f32_e32 v100, v151, v100
	v_add_f32_e32 v101, v156, v101
	v_exp_f32_e32 v78, v78
	v_exp_f32_e32 v79, v79
	v_exp_f32_e32 v80, v80
	v_exp_f32_e32 v81, v81
	v_add_f32_e32 v98, v152, v98
	v_add_f32_e32 v99, v155, v99
	v_add_f32_e32 v100, v153, v100
	v_add_f32_e32 v101, v154, v101
	v_add_f32_e32 v98, v66, v98
	v_add_f32_e32 v99, v67, v99
	v_add_f32_e32 v100, v68, v100
	v_add_f32_e32 v101, v69, v101
	v_add_f32_e32 v98, v70, v98
	v_add_f32_e32 v99, v71, v99
	v_add_f32_e32 v100, v72, v100
	v_add_f32_e32 v101, v73, v101
	v_add_f32_e32 v98, v74, v98
	v_add_f32_e32 v99, v75, v99
	v_add_f32_e32 v100, v76, v100
	v_add_f32_e32 v101, v77, v101
	v_add_f32_e32 v98, v78, v98
	v_add_f32_e32 v99, v79, v99
	v_add_f32_e32 v100, v80, v100
	v_add_f32_e32 v101, v81, v101
	v_add_f32_e32 v98, v98, v99
	v_add_f32_e32 v99, v100, v101
	v_add_f32_e32 v224, v98, v99
	v_mov_b32_e32 v225, v224
	v_cvt_pk_bf16_f32 v146, v146, v161
	v_cvt_pk_bf16_f32 v147, v147, v160
	v_cvt_pk_bf16_f32 v148, v148, v159
	v_cvt_pk_bf16_f32 v149, v149, v158
	v_cvt_pk_bf16_f32 v150, v150, v157
	v_cvt_pk_bf16_f32 v151, v151, v156
	v_cvt_pk_bf16_f32 v152, v152, v155
	v_cvt_pk_bf16_f32 v153, v153, v154
	v_cvt_pk_bf16_f32 v158, v66, v67
	v_cvt_pk_bf16_f32 v159, v68, v69
	v_cvt_pk_bf16_f32 v160, v70, v71
	v_cvt_pk_bf16_f32 v161, v72, v73
	v_cvt_pk_bf16_f32 v154, v74, v75
	v_cvt_pk_bf16_f32 v155, v76, v77
	v_cvt_pk_bf16_f32 v156, v78, v79
	v_cvt_pk_bf16_f32 v157, v80, v81
	s_nop 1
	v_permlane32_swap_b32_e32 v224, v225
	v_cmp_neq_f32_e64 s[6:7], v229, -v226
	s_cmp_eq_u64 s[6:7], 0
	s_cselect_b64 s[6:7], -1, 0
	v_cndmask_b32_e64 v81, -v226, v97, s[6:7]
	v_cndmask_b32_e64 v80, -v226, v96, s[6:7]
	v_cndmask_b32_e64 v79, -v226, v95, s[6:7]
	v_cndmask_b32_e64 v78, -v226, v94, s[6:7]
	v_cndmask_b32_e64 v77, -v226, v93, s[6:7]
	v_cndmask_b32_e64 v76, -v226, v92, s[6:7]
	v_cndmask_b32_e64 v75, -v226, v91, s[6:7]
	v_cndmask_b32_e64 v74, -v226, v90, s[6:7]
	v_cndmask_b32_e64 v73, -v226, v89, s[6:7]
	v_cndmask_b32_e64 v72, -v226, v88, s[6:7]
	v_cndmask_b32_e64 v71, -v226, v87, s[6:7]
	v_cndmask_b32_e64 v70, -v226, v86, s[6:7]
	v_cndmask_b32_e64 v69, -v226, v85, s[6:7]
	v_cndmask_b32_e64 v68, -v226, v84, s[6:7]
	v_cndmask_b32_e64 v67, -v226, v83, s[6:7]
	v_cndmask_b32_e64 v66, -v226, v82, s[6:7]
	ds_read_b128 v[82:85], v221 offset:0
	ds_read_b128 v[162:165], v221 offset:0x3000
	ds_read_b128 v[166:169], v220 offset:0
	ds_read_b128 v[170:173], v220 offset:0x3000
	s_waitcnt lgkmcnt(2)
	s_nop 1
	v_mfma_f32_32x32x16_bf16 v[98:113], v[82:85], v[142:145], v[66:81]
	v_mfma_f32_32x32x16_bf16 v[82:97], v[162:165], v[142:145], v[66:81]
	ds_read_b128 v[162:165], v219 offset:0
	ds_read_b128 v[174:177], v219 offset:0x3000
	s_waitcnt lgkmcnt(2)
	v_mfma_f32_32x32x16_bf16 v[98:113], v[166:169], v[138:141], v[98:113]
	ds_read_b128 v[166:169], v218 offset:0
	v_mfma_f32_32x32x16_bf16 v[82:97], v[170:173], v[138:141], v[82:97]
	ds_read_b128 v[170:173], v218 offset:0x3000
	s_waitcnt lgkmcnt(2)
	v_mfma_f32_32x32x16_bf16 v[98:113], v[162:165], v[134:137], v[98:113]
	ds_read_b128 v[162:165], v221 offset:0x80
	v_mfma_f32_32x32x16_bf16 v[82:97], v[174:177], v[134:137], v[82:97]
	ds_read_b128 v[174:177], v221 offset:0x3080
	s_waitcnt lgkmcnt(2)
	v_mfma_f32_32x32x16_bf16 v[98:113], v[166:169], v[130:133], v[98:113]
	ds_read_b128 v[166:169], v220 offset:0x80
	v_mfma_f32_32x32x16_bf16 v[82:97], v[170:173], v[130:133], v[82:97]
	ds_read_b128 v[170:173], v220 offset:0x3080
	s_waitcnt lgkmcnt(2)
	v_mfma_f32_32x32x16_bf16 v[98:113], v[162:165], v[126:129], v[98:113]
	ds_read_b128 v[162:165], v219 offset:0x80
	v_mfma_f32_32x32x16_bf16 v[82:97], v[174:177], v[126:129], v[82:97]
	ds_read_b128 v[174:177], v219 offset:0x3080
	s_waitcnt lgkmcnt(2)
	v_mfma_f32_32x32x16_bf16 v[98:113], v[166:169], v[122:125], v[98:113]
	ds_read_b128 v[166:169], v218 offset:0x80
	v_mfma_f32_32x32x16_bf16 v[82:97], v[170:173], v[122:125], v[82:97]
	ds_read_b128 v[170:173], v218 offset:0x3080
	s_waitcnt lgkmcnt(2)
	v_mfma_f32_32x32x16_bf16 v[98:113], v[162:165], v[118:121], v[98:113]
	ds_read_b128 v[162:165], v221 offset:0x100
	v_mfma_f32_32x32x16_bf16 v[82:97], v[174:177], v[118:121], v[82:97]
	ds_read_b128 v[174:177], v221 offset:0x3100
	ds_read_b128 v[178:181], v199 offset:0
	s_waitcnt lgkmcnt(3)
	v_mfma_f32_32x32x16_bf16 v[98:113], v[166:169], v[114:117], v[98:113]
	ds_read_b128 v[166:169], v220 offset:0x100
	v_mfma_f32_32x32x16_bf16 v[82:97], v[170:173], v[114:117], v[82:97]
	ds_read_b128 v[170:173], v220 offset:0x3100
	ds_read_b128 v[230:233], v199 offset:0x400
	s_waitcnt lgkmcnt(3)
	v_mfma_f32_32x32x16_bf16 v[98:113], v[162:165], v[178:181], v[98:113]
	ds_read_b128 v[162:165], v219 offset:0x100
	v_mfma_f32_32x32x16_bf16 v[82:97], v[174:177], v[178:181], v[82:97]
	ds_read_b128 v[174:177], v219 offset:0x3100
	ds_read_b128 v[178:181], v199 offset:0x800
	s_waitcnt lgkmcnt(3)
	v_mfma_f32_32x32x16_bf16 v[98:113], v[166:169], v[230:233], v[98:113]
	ds_read_b128 v[166:169], v218 offset:0x100
	v_mfma_f32_32x32x16_bf16 v[82:97], v[170:173], v[230:233], v[82:97]
	ds_read_b128 v[170:173], v218 offset:0x3100
	ds_read_b128 v[230:233], v199 offset:0xc00
	s_waitcnt lgkmcnt(3)
	v_mfma_f32_32x32x16_bf16 v[98:113], v[162:165], v[178:181], v[98:113]
	s_waitcnt lgkmcnt(0)
	v_mfma_f32_32x32x16_bf16 v[82:97], v[174:177], v[178:181], v[82:97]
	v_mfma_f32_32x32x16_bf16 v[98:113], v[166:169], v[230:233], v[98:113]
	v_mfma_f32_32x32x16_bf16 v[82:97], v[170:173], v[230:233], v[82:97]
	s_nop 10
	v_max_f32_e32 v162, v98, v102
	v_max_f32_e32 v163, v99, v103
	v_max_f32_e32 v164, v101, v105
	v_max3_f32 v165, v100, v104, v108
	v_max3_f32 v164, v164, v109, v113
	v_max3_f32 v162, v162, v106, v110
	v_max3_f32 v163, v163, v107, v111
	v_max3_f32 v165, v165, v112, v84
	v_max3_f32 v164, v164, v85, v89
	v_max3_f32 v162, v162, v82, v86
	v_max3_f32 v163, v163, v83, v87
	v_max3_f32 v165, v165, v88, v92
	v_max3_f32 v164, v164, v93, v97
	v_max3_f32 v162, v162, v90, v94
	v_max3_f32 v163, v163, v91, v95
	v_max3_f32 v164, v165, v96, v164
	v_max3_f32 v162, v162, v163, v164
	v_mov_b32_e32 v163, v162
	s_nop 1
	v_permlane32_swap_b32_e32 v162, v163
	v_max_f32_e32 v162, v162, v163
	v_cmp_ge_f32_e32 vcc, s48, v162
	s_cmp_eq_u64 vcc, exec
	s_cbranch_scc0 .LBB0_374
	v_mov_b32_e32 v228, v226
	v_mov_b32_e32 v227, 1.0

; template <bool FIRST>
; __device__ __forceinline__ void partialSM(f32x16& p0, f32x16& p1, float& mC, float& alpha) {
;     ...
;   for (int r = 0; r < 16; ++r) p0[r] = __builtin_amdgcn_exp2f(p0[r]);
; }
; template <bool EXP1 = true>
; __device__ __forceinline__ void finishSM(f32x16& p0, f32x16& p1, float alpha, float& l_reg, bf16x8& pa0, bf16x8& pa1, bf16x8& pa2, bf16x8& pa3) {
;   if constexpr (EXP1) {
; #pragma unroll
;   for (int r = 0; r < 16; ++r) p1[r] = __builtin_amdgcn_exp2f(p1[r]);
;   }
;   float sm_[4] = {p0[0], p0[1], p0[2], p0[3]};
; #pragma unroll
;   for (int r = 4; r < 16; ++r) sm_[r & 3] += p0[r];
; #pragma unroll
;   for (int r = 0; r < 16; ++r) sm_[r & 3] += p1[r];
;   float ps = (sm_[0] + sm_[1]) + (sm_[2] + sm_[3]);
;   { auto rr = __builtin_amdgcn_permlane32_swap(__float_as_uint(ps), __float_as_uint(ps), false, false);
;     ps = __uint_as_float(rr[0]) + __uint_as_float(rr[1]); }
;   l_reg = l_reg * alpha + ps;
.LBB0_366:
	v_exp_f32_e32 v146, v98
	v_exp_f32_e32 v153, v99
	v_exp_f32_e32 v147, v100
	v_exp_f32_e32 v152, v101
	v_exp_f32_e32 v148, v102
	v_exp_f32_e32 v151, v103
	v_exp_f32_e32 v149, v104
	v_exp_f32_e32 v150, v105
	v_exp_f32_e32 v103, v106
	v_exp_f32_e32 v105, v107
	v_exp_f32_e32 v101, v108
	v_exp_f32_e32 v104, v109
	v_exp_f32_e32 v99, v110
	v_exp_f32_e32 v102, v111
	v_exp_f32_e32 v98, v112
	v_exp_f32_e32 v100, v113
	v_xor_b32_e32 v106, 0x80000000, v226
	v_exp_f32_e32 v82, v82
	v_exp_f32_e32 v83, v83
	v_exp_f32_e32 v84, v84
	v_exp_f32_e32 v85, v85
	v_cndmask_b32_e64 v229, v106, v229, s[6:7]
	v_exp_f32_e32 v86, v86
	v_exp_f32_e32 v87, v87
	v_exp_f32_e32 v88, v88
	v_exp_f32_e32 v89, v89
	v_add_f32_e32 v106, v148, v146
	v_add_f32_e32 v107, v151, v153
	v_add_f32_e32 v108, v149, v147
	v_add_f32_e32 v109, v150, v152
	v_exp_f32_e32 v90, v90
	v_exp_f32_e32 v91, v91
	v_exp_f32_e32 v92, v92
	v_exp_f32_e32 v93, v93
	v_add_f32_e32 v106, v103, v106
	v_add_f32_e32 v107, v105, v107
	v_add_f32_e32 v108, v101, v108
	v_add_f32_e32 v109, v104, v109
	v_exp_f32_e32 v94, v94
	v_exp_f32_e32 v95, v95
	v_exp_f32_e32 v96, v96
	v_exp_f32_e32 v97, v97
	v_add_f32_e32 v106, v99, v106
	v_add_f32_e32 v107, v102, v107
	v_add_f32_e32 v108, v98, v108
	v_add_f32_e32 v109, v100, v109
	v_add_f32_e32 v106, v82, v106
	v_add_f32_e32 v107, v107, v83
	v_add_f32_e32 v108, v108, v84
	v_add_f32_e32 v109, v109, v85
	v_add_f32_e32 v106, v86, v106
	v_add_f32_e32 v107, v87, v107
	v_add_f32_e32 v108, v88, v108
	v_add_f32_e32 v109, v89, v109
	v_add_f32_e32 v106, v90, v106
	v_add_f32_e32 v107, v91, v107
	v_add_f32_e32 v108, v92, v108
	v_add_f32_e32 v109, v93, v109
	v_add_f32_e32 v106, v94, v106
	v_add_f32_e32 v107, v95, v107
	v_add_f32_e32 v108, v96, v108
	v_add_f32_e32 v109, v97, v109
	v_add_f32_e32 v106, v106, v107
	v_add_f32_e32 v107, v108, v109
	v_add_f32_e32 v230, v106, v107
	s_waitcnt lgkmcnt(0)
	s_barrier
; __device__ __forceinline__ void qkt12_roll(f32x16& p0, f32x16& p1, const f32x16& negm, int kb, int qa, const bf16x8* qr) {
;   const int a0 = kb ^ (0 << 5); const bf16x8 x0 = lds_rd128<0>(a0), y0 = lds_rd128<12288>(a0);
;   const int a1 = kb ^ (1 << 5); const bf16x8 x1 = lds_rd128<0>(a1), y1 = lds_rd128<12288>(a1);
;   asm volatile("s_waitcnt lgkmcnt(2)" ::: "memory"); SBAR();
;   p0 = __builtin_amdgcn_mfma_f32_32x32x16_bf16(x0, qr[0], negm, 0, 0, 0); p1 = __builtin_amdgcn_mfma_f32_32x32x16_bf16(y0, qr[0], negm, 0, 0, 0);
;   const int a2 = kb ^ (2 << 5); const bf16x8 x2 = lds_rd128<0>(a2), y2 = lds_rd128<12288>(a2);
;   asm volatile("s_waitcnt lgkmcnt(2)" ::: "memory"); SBAR();
;   p0 = __builtin_amdgcn_mfma_f32_32x32x16_bf16(x1, qr[1], p0, 0, 0, 0); p1 = __builtin_amdgcn_mfma_f32_32x32x16_bf16(y1, qr[1], p1, 0, 0, 0);
;   const int a3 = kb ^ (3 << 5); const bf16x8 x3 = lds_rd128<0>(a3), y3 = lds_rd128<12288>(a3);
;   asm volatile("s_waitcnt lgkmcnt(2)" ::: "memory"); SBAR();
;   p0 = __builtin_amdgcn_mfma_f32_32x32x16_bf16(x2, qr[2], p0, 0, 0, 0); p1 = __builtin_amdgcn_mfma_f32_32x32x16_bf16(y2, qr[2], p1, 0, 0, 0);
;   const int a4 = kb ^ (0 << 5); const bf16x8 x4 = lds_rd128<128>(a4), y4 = lds_rd128<12416>(a4);
;   asm volatile("s_waitcnt lgkmcnt(2)" ::: "memory"); SBAR();
;   p0 = __builtin_amdgcn_mfma_f32_32x32x16_bf16(x3, qr[3], p0, 0, 0, 0); p1 = __builtin_amdgcn_mfma_f32_32x32x16_bf16(y3, qr[3], p1, 0, 0, 0);
;   const int a5 = kb ^ (1 << 5); const bf16x8 x5 = lds_rd128<128>(a5), y5 = lds_rd128<12416>(a5);
;   asm volatile("s_waitcnt lgkmcnt(2)" ::: "memory"); SBAR();
;   p0 = __builtin_amdgcn_mfma_f32_32x32x16_bf16(x4, qr[4], p0, 0, 0, 0); p1 = __builtin_amdgcn_mfma_f32_32x32x16_bf16(y4, qr[4], p1, 0, 0, 0);
;   const int a6 = kb ^ (2 << 5); const bf16x8 x6 = lds_rd128<128>(a6), y6 = lds_rd128<12416>(a6);
;   asm volatile("s_waitcnt lgkmcnt(2)" ::: "memory"); SBAR();
;   p0 = __builtin_amdgcn_mfma_f32_32x32x16_bf16(x5, qr[5], p0, 0, 0, 0); p1 = __builtin_amdgcn_mfma_f32_32x32x16_bf16(y5, qr[5], p1, 0, 0, 0);
;   const int a7 = kb ^ (3 << 5); const bf16x8 x7 = lds_rd128<128>(a7), y7 = lds_rd128<12416>(a7);
;   asm volatile("s_waitcnt lgkmcnt(2)" ::: "memory"); SBAR();
;   p0 = __builtin_amdgcn_mfma_f32_32x32x16_bf16(x6, qr[6], p0, 0, 0, 0); p1 = __builtin_amdgcn_mfma_f32_32x32x16_bf16(y6, qr[6], p1, 0, 0, 0);
	v_mov_b32_e32 v231, v230
	v_cvt_pk_bf16_f32 v146, v146, v153
	v_cvt_pk_bf16_f32 v147, v147, v152
	v_cvt_pk_bf16_f32 v148, v148, v151
	v_cvt_pk_bf16_f32 v149, v149, v150
	v_cvt_pk_bf16_f32 v150, v103, v105
	v_cvt_pk_bf16_f32 v151, v101, v104
	v_cvt_pk_bf16_f32 v152, v99, v102
	v_cvt_pk_bf16_f32 v153, v98, v100
	v_cvt_pk_bf16_f32 v158, v82, v83
	v_cvt_pk_bf16_f32 v159, v84, v85
	v_cvt_pk_bf16_f32 v160, v86, v87
	v_cvt_pk_bf16_f32 v161, v88, v89
	v_cvt_pk_bf16_f32 v154, v90, v91
	v_cvt_pk_bf16_f32 v155, v92, v93
	v_cvt_pk_bf16_f32 v156, v94, v95
	v_cvt_pk_bf16_f32 v157, v96, v97
	s_nop 1
	v_permlane32_swap_b32_e32 v230, v231
	v_cmp_neq_f32_e64 s[6:7], v229, -v228
	s_cmp_eq_u64 s[6:7], 0
	s_cselect_b64 s[6:7], -1, 0
	v_cndmask_b32_e64 v97, -v228, v81, s[6:7]
	v_cndmask_b32_e64 v96, -v228, v80, s[6:7]
	v_cndmask_b32_e64 v95, -v228, v79, s[6:7]
	v_cndmask_b32_e64 v94, -v228, v78, s[6:7]
	v_cndmask_b32_e64 v93, -v228, v77, s[6:7]
	v_cndmask_b32_e64 v92, -v228, v76, s[6:7]
	v_cndmask_b32_e64 v91, -v228, v75, s[6:7]
	v_cndmask_b32_e64 v90, -v228, v74, s[6:7]
	v_cndmask_b32_e64 v89, -v228, v73, s[6:7]
	v_cndmask_b32_e64 v88, -v228, v72, s[6:7]
	v_cndmask_b32_e64 v87, -v228, v71, s[6:7]
	v_cndmask_b32_e64 v86, -v228, v70, s[6:7]
	v_cndmask_b32_e64 v85, -v228, v69, s[6:7]
	v_cndmask_b32_e64 v84, -v228, v68, s[6:7]
	v_cndmask_b32_e64 v83, -v228, v67, s[6:7]
	v_cndmask_b32_e64 v82, -v228, v66, s[6:7]
	ds_read_b128 v[66:69], v209 offset:0
	ds_read_b128 v[162:165], v209 offset:0x3000
	ds_read_b128 v[166:169], v215 offset:0
	ds_read_b128 v[170:173], v215 offset:0x3000
	s_waitcnt lgkmcnt(2)
	s_nop 1
	v_mfma_f32_32x32x16_bf16 v[98:113], v[66:69], v[142:145], v[82:97]
	v_mfma_f32_32x32x16_bf16 v[66:81], v[162:165], v[142:145], v[82:97]
	ds_read_b128 v[162:165], v216 offset:0
	ds_read_b128 v[174:177], v216 offset:0x3000
	s_waitcnt lgkmcnt(2)
	v_mfma_f32_32x32x16_bf16 v[98:113], v[166:169], v[138:141], v[98:113]
	ds_read_b128 v[166:169], v217 offset:0
	v_mfma_f32_32x32x16_bf16 v[66:81], v[170:173], v[138:141], v[66:81]
	ds_read_b128 v[170:173], v217 offset:0x3000
	s_waitcnt lgkmcnt(2)
	v_mfma_f32_32x32x16_bf16 v[98:113], v[162:165], v[134:137], v[98:113]
	ds_read_b128 v[162:165], v209 offset:0x80
	v_mfma_f32_32x32x16_bf16 v[66:81], v[174:177], v[134:137], v[66:81]
	ds_read_b128 v[174:177], v209 offset:0x3080
	s_waitcnt lgkmcnt(2)
	v_mfma_f32_32x32x16_bf16 v[98:113], v[166:169], v[130:133], v[98:113]
	ds_read_b128 v[166:169], v215 offset:0x80
	v_mfma_f32_32x32x16_bf16 v[66:81], v[170:173], v[130:133], v[66:81]
	ds_read_b128 v[170:173], v215 offset:0x3080
	s_waitcnt lgkmcnt(2)
	v_mfma_f32_32x32x16_bf16 v[98:113], v[162:165], v[126:129], v[98:113]
	ds_read_b128 v[162:165], v216 offset:0x80
	v_mfma_f32_32x32x16_bf16 v[66:81], v[174:177], v[126:129], v[66:81]
	ds_read_b128 v[174:177], v216 offset:0x3080
	s_waitcnt lgkmcnt(2)
	v_mfma_f32_32x32x16_bf16 v[98:113], v[166:169], v[122:125], v[98:113]
	ds_read_b128 v[166:169], v217 offset:0x80
	v_mfma_f32_32x32x16_bf16 v[66:81], v[170:173], v[122:125], v[66:81]
	ds_read_b128 v[170:173], v217 offset:0x3080
	s_waitcnt lgkmcnt(2)
	v_mfma_f32_32x32x16_bf16 v[98:113], v[162:165], v[118:121], v[98:113]
	ds_read_b128 v[162:165], v209 offset:0x100
	v_mfma_f32_32x32x16_bf16 v[66:81], v[174:177], v[118:121], v[66:81]
	ds_read_b128 v[174:177], v209 offset:0x3100
	ds_read_b128 v[178:181], v199 offset:0
	s_waitcnt lgkmcnt(3)
	v_mfma_f32_32x32x16_bf16 v[98:113], v[166:169], v[114:117], v[98:113]
	ds_read_b128 v[166:169], v215 offset:0x100
	v_mfma_f32_32x32x16_bf16 v[66:81], v[170:173], v[114:117], v[66:81]
	ds_read_b128 v[170:173], v215 offset:0x3100
	ds_read_b128 v[232:235], v199 offset:0x400
	s_waitcnt lgkmcnt(3)
	v_mfma_f32_32x32x16_bf16 v[98:113], v[162:165], v[178:181], v[98:113]
	ds_read_b128 v[162:165], v216 offset:0x100
	v_mfma_f32_32x32x16_bf16 v[66:81], v[174:177], v[178:181], v[66:81]
	ds_read_b128 v[174:177], v216 offset:0x3100
	ds_read_b128 v[178:181], v199 offset:0x800
	s_waitcnt lgkmcnt(3)
	v_mfma_f32_32x32x16_bf16 v[98:113], v[166:169], v[232:235], v[98:113]
	ds_read_b128 v[166:169], v217 offset:0x100
	v_mfma_f32_32x32x16_bf16 v[66:81], v[170:173], v[232:235], v[66:81]
	ds_read_b128 v[170:173], v217 offset:0x3100
	ds_read_b128 v[232:235], v199 offset:0xc00
	s_waitcnt lgkmcnt(3)
	v_mfma_f32_32x32x16_bf16 v[98:113], v[162:165], v[178:181], v[98:113]
	s_waitcnt lgkmcnt(0)
	v_mfma_f32_32x32x16_bf16 v[66:81], v[174:177], v[178:181], v[66:81]
	v_mfma_f32_32x32x16_bf16 v[98:113], v[166:169], v[232:235], v[98:113]
	v_mfma_f32_32x32x16_bf16 v[66:81], v[170:173], v[232:235], v[66:81]
	s_nop 10
	v_max_f32_e32 v162, v98, v102
	v_max_f32_e32 v163, v99, v103
	v_max_f32_e32 v164, v101, v105
	v_max3_f32 v165, v100, v104, v108
	v_max3_f32 v164, v164, v109, v113
	v_max3_f32 v162, v162, v106, v110
	v_max3_f32 v163, v163, v107, v111
	v_max3_f32 v165, v165, v112, v68
	v_max3_f32 v164, v164, v69, v73
	v_max3_f32 v162, v162, v66, v70
	v_max3_f32 v163, v163, v67, v71
	v_max3_f32 v165, v165, v72, v76
	v_max3_f32 v164, v164, v77, v81
	v_max3_f32 v162, v162, v74, v78
	v_max3_f32 v163, v163, v75, v79
	v_max3_f32 v164, v165, v80, v164
	v_max3_f32 v162, v162, v163, v164
	v_mov_b32_e32 v163, v162
	s_nop 1
	v_permlane32_swap_b32_e32 v162, v163
	v_max_f32_e32 v162, v162, v163
	v_cmp_ge_f32_e32 vcc, s48, v162
	s_cmp_eq_u64 vcc, exec
	v_mov_b32_e32 v223, 1.0
	s_cbranch_scc0 .LBB0_375
	v_mov_b32_e32 v226, v228

; __device__ __forceinline__ void qkt12_roll(f32x16& p0, f32x16& p1, const f32x16& negm, int kb, int qa, const bf16x8* qr) {
;   const int a0 = kb ^ (0 << 5); const bf16x8 x0 = lds_rd128<0>(a0), y0 = lds_rd128<12288>(a0);
;   const int a1 = kb ^ (1 << 5); const bf16x8 x1 = lds_rd128<0>(a1), y1 = lds_rd128<12288>(a1);
;   asm volatile("s_waitcnt lgkmcnt(2)" ::: "memory"); SBAR();
;   p0 = __builtin_amdgcn_mfma_f32_32x32x16_bf16(x0, qr[0], negm, 0, 0, 0); p1 = __builtin_amdgcn_mfma_f32_32x32x16_bf16(y0, qr[0], negm, 0, 0, 0);
;   const int a2 = kb ^ (2 << 5); const bf16x8 x2 = lds_rd128<0>(a2), y2 = lds_rd128<12288>(a2);
;   asm volatile("s_waitcnt lgkmcnt(2)" ::: "memory"); SBAR();
;   p0 = __builtin_amdgcn_mfma_f32_32x32x16_bf16(x1, qr[1], p0, 0, 0, 0); p1 = __builtin_amdgcn_mfma_f32_32x32x16_bf16(y1, qr[1], p1, 0, 0, 0);
;   const int a3 = kb ^ (3 << 5); const bf16x8 x3 = lds_rd128<0>(a3), y3 = lds_rd128<12288>(a3);
;   asm volatile("s_waitcnt lgkmcnt(2)" ::: "memory"); SBAR();
;   p0 = __builtin_amdgcn_mfma_f32_32x32x16_bf16(x2, qr[2], p0, 0, 0, 0); p1 = __builtin_amdgcn_mfma_f32_32x32x16_bf16(y2, qr[2], p1, 0, 0, 0);
;   const int a4 = kb ^ (0 << 5); const bf16x8 x4 = lds_rd128<128>(a4), y4 = lds_rd128<12416>(a4);
;   asm volatile("s_waitcnt lgkmcnt(2)" ::: "memory"); SBAR();
;   p0 = __builtin_amdgcn_mfma_f32_32x32x16_bf16(x3, qr[3], p0, 0, 0, 0); p1 = __builtin_amdgcn_mfma_f32_32x32x16_bf16(y3, qr[3], p1, 0, 0, 0);
;   const int a5 = kb ^ (1 << 5); const bf16x8 x5 = lds_rd128<128>(a5), y5 = lds_rd128<12416>(a5);
;   asm volatile("s_waitcnt lgkmcnt(2)" ::: "memory"); SBAR();
;   p0 = __builtin_amdgcn_mfma_f32_32x32x16_bf16(x4, qr[4], p0, 0, 0, 0); p1 = __builtin_amdgcn_mfma_f32_32x32x16_bf16(y4, qr[4], p1, 0, 0, 0);
;   const int a6 = kb ^ (2 << 5); const bf16x8 x6 = lds_rd128<128>(a6), y6 = lds_rd128<12416>(a6);
;   asm volatile("s_waitcnt lgkmcnt(2)" ::: "memory"); SBAR();
;   p0 = __builtin_amdgcn_mfma_f32_32x32x16_bf16(x5, qr[5], p0, 0, 0, 0); p1 = __builtin_amdgcn_mfma_f32_32x32x16_bf16(y5, qr[5], p1, 0, 0, 0);
;   const int a7 = kb ^ (3 << 5); const bf16x8 x7 = lds_rd128<128>(a7), y7 = lds_rd128<12416>(a7);
;   asm volatile("s_waitcnt lgkmcnt(2)" ::: "memory"); SBAR();
;   p0 = __builtin_amdgcn_mfma_f32_32x32x16_bf16(x6, qr[6], p0, 0, 0, 0); p1 = __builtin_amdgcn_mfma_f32_32x32x16_bf16(y6, qr[6], p1, 0, 0, 0);
.LBB0_386:
	v_cmp_neq_f32_e64 s[6:7], v228, -v225
	s_cmp_eq_u64 s[6:7], 0
	s_cselect_b64 s[6:7], -1, 0
	v_cndmask_b32_e64 v113, -v225, v113, s[6:7]
	v_cndmask_b32_e64 v112, -v225, v112, s[6:7]
	v_cndmask_b32_e64 v111, -v225, v111, s[6:7]
	v_cndmask_b32_e64 v110, -v225, v110, s[6:7]
	v_cndmask_b32_e64 v109, -v225, v109, s[6:7]
	v_cndmask_b32_e64 v108, -v225, v108, s[6:7]
	v_cndmask_b32_e64 v107, -v225, v107, s[6:7]
	v_cndmask_b32_e64 v106, -v225, v106, s[6:7]
	v_cndmask_b32_e64 v105, -v225, v105, s[6:7]
	v_cndmask_b32_e64 v104, -v225, v104, s[6:7]
	v_cndmask_b32_e64 v103, -v225, v103, s[6:7]
	v_cndmask_b32_e64 v102, -v225, v102, s[6:7]
	v_cndmask_b32_e64 v101, -v225, v101, s[6:7]
	v_cndmask_b32_e64 v100, -v225, v100, s[6:7]
	v_cndmask_b32_e64 v99, -v225, v99, s[6:7]
	v_cndmask_b32_e64 v98, -v225, v98, s[6:7]
	ds_read_b128 v[82:85], v221 offset:0
	ds_read_b128 v[230:233], v221 offset:0x3000
	ds_read_b128 v[234:237], v220 offset:0
	ds_read_b128 v[238:241], v220 offset:0x3000
	s_waitcnt lgkmcnt(2)
	s_nop 1
	v_mfma_f32_32x32x16_bf16 v[114:129], v[82:85], v[158:161], v[98:113]
	v_mfma_f32_32x32x16_bf16 v[82:97], v[230:233], v[158:161], v[98:113]
	ds_read_b128 v[230:233], v219 offset:0
	ds_read_b128 v[242:245], v219 offset:0x3000
	s_waitcnt lgkmcnt(2)
	v_mfma_f32_32x32x16_bf16 v[114:129], v[234:237], v[154:157], v[114:129]
	ds_read_b128 v[234:237], v218 offset:0
	v_mfma_f32_32x32x16_bf16 v[82:97], v[238:241], v[154:157], v[82:97]
	ds_read_b128 v[238:241], v218 offset:0x3000
	s_waitcnt lgkmcnt(2)
	v_mfma_f32_32x32x16_bf16 v[114:129], v[230:233], v[150:153], v[114:129]
	ds_read_b128 v[230:233], v221 offset:0x80
	v_mfma_f32_32x32x16_bf16 v[82:97], v[242:245], v[150:153], v[82:97]
	ds_read_b128 v[242:245], v221 offset:0x3080
	s_waitcnt lgkmcnt(2)
	v_mfma_f32_32x32x16_bf16 v[114:129], v[234:237], v[146:149], v[114:129]
	ds_read_b128 v[234:237], v220 offset:0x80
	v_mfma_f32_32x32x16_bf16 v[82:97], v[238:241], v[146:149], v[82:97]
	ds_read_b128 v[238:241], v220 offset:0x3080
	s_waitcnt lgkmcnt(2)
	v_mfma_f32_32x32x16_bf16 v[114:129], v[230:233], v[142:145], v[114:129]
	ds_read_b128 v[230:233], v219 offset:0x80
	v_mfma_f32_32x32x16_bf16 v[82:97], v[242:245], v[142:145], v[82:97]
	ds_read_b128 v[242:245], v219 offset:0x3080
	s_waitcnt lgkmcnt(2)
	v_mfma_f32_32x32x16_bf16 v[114:129], v[234:237], v[138:141], v[114:129]
	ds_read_b128 v[234:237], v218 offset:0x80
	v_mfma_f32_32x32x16_bf16 v[82:97], v[238:241], v[138:141], v[82:97]
	ds_read_b128 v[238:241], v218 offset:0x3080
	s_waitcnt lgkmcnt(2)
	v_mfma_f32_32x32x16_bf16 v[114:129], v[230:233], v[134:137], v[114:129]
	ds_read_b128 v[230:233], v221 offset:0x100
	v_mfma_f32_32x32x16_bf16 v[82:97], v[242:245], v[134:137], v[82:97]
	ds_read_b128 v[242:245], v221 offset:0x3100
	ds_read_b128 v[246:249], v199 offset:0
	s_waitcnt lgkmcnt(3)
	v_mfma_f32_32x32x16_bf16 v[114:129], v[234:237], v[130:133], v[114:129]
	ds_read_b128 v[234:237], v220 offset:0x100
	v_mfma_f32_32x32x16_bf16 v[82:97], v[238:241], v[130:133], v[82:97]
	ds_read_b128 v[238:241], v220 offset:0x3100
	ds_read_b128 v[250:253], v199 offset:0x400
	s_waitcnt lgkmcnt(3)
	v_mfma_f32_32x32x16_bf16 v[114:129], v[230:233], v[246:249], v[114:129]
	ds_read_b128 v[230:233], v219 offset:0x100
	v_mfma_f32_32x32x16_bf16 v[82:97], v[242:245], v[246:249], v[82:97]
	ds_read_b128 v[242:245], v219 offset:0x3100
	ds_read_b128 v[246:249], v199 offset:0x800
	s_waitcnt lgkmcnt(3)
	v_mfma_f32_32x32x16_bf16 v[114:129], v[234:237], v[250:253], v[114:129]
	ds_read_b128 v[234:237], v218 offset:0x100
	v_mfma_f32_32x32x16_bf16 v[82:97], v[238:241], v[250:253], v[82:97]
	ds_read_b128 v[238:241], v218 offset:0x3100
	ds_read_b128 v[250:253], v199 offset:0xc00
	s_waitcnt lgkmcnt(3)
	v_mfma_f32_32x32x16_bf16 v[114:129], v[230:233], v[246:249], v[114:129]
	s_waitcnt lgkmcnt(0)
; __device__ __forceinline__ void pv_d0(f32x16* o, int vb, bf16x8 pa0, bf16x8 pa1, bf16x8 pa2, bf16x8 pa3) {
;     ...
;   const s16x4 l0 = tr_read<v_rd_off(0, 0, 0)>(vb), h0 = tr_read<v_rd_off(0, 0, 1)>(vb);
;   const s16x4 l1 = tr_read<v_rd_off(0, 1, 0)>(vb), h1 = tr_read<v_rd_off(0, 1, 1)>(vb);
;   const s16x4 l2 = tr_read<v_rd_off(0, 2, 0)>(vb), h2 = tr_read<v_rd_off(0, 2, 1)>(vb);
;   const s16x4 l3 = tr_read<v_rd_off(0, 3, 0)>(vb), h3 = tr_read<v_rd_off(0, 3, 1)>(vb);
;   const s16x4 l4 = tr_read<v_rd_off(1, 0, 0)>(vb), h4 = tr_read<v_rd_off(1, 0, 1)>(vb);
;   asm volatile("s_waitcnt lgkmcnt(8)" ::: "memory"); SBAR();
;   o[0] = __builtin_amdgcn_mfma_f32_32x32x16_bf16(pa0, PK(l0, h0), o[0], 0, 0, 0);
;   const s16x4 l5 = tr_read<v_rd_off(1, 1, 0)>(vb), h5 = tr_read<v_rd_off(1, 1, 1)>(vb);
;   asm volatile("s_waitcnt lgkmcnt(8)" ::: "memory"); SBAR();
;   o[0] = __builtin_amdgcn_mfma_f32_32x32x16_bf16(pa1, PK(l1, h1), o[0], 0, 0, 0);
;   const s16x4 l6 = tr_read<v_rd_off(1, 2, 0)>(vb), h6 = tr_read<v_rd_off(1, 2, 1)>(vb);
;   asm volatile("s_waitcnt lgkmcnt(8)" ::: "memory"); SBAR();
;   o[0] = __builtin_amdgcn_mfma_f32_32x32x16_bf16(pa2, PK(l2, h2), o[0], 0, 0, 0);
;   const s16x4 l7 = tr_read<v_rd_off(1, 3, 0)>(vb), h7 = tr_read<v_rd_off(1, 3, 1)>(vb);
;   asm volatile("s_waitcnt lgkmcnt(8)" ::: "memory"); SBAR();
;   o[0] = __builtin_amdgcn_mfma_f32_32x32x16_bf16(pa3, PK(l3, h3), o[0], 0, 0, 0);
;   const s16x4 l8 = tr_read<v_rd_off(2, 0, 0)>(vb), h8 = tr_read<v_rd_off(2, 0, 1)>(vb);
;   asm volatile("s_waitcnt lgkmcnt(8)" ::: "memory"); SBAR();
;   o[1] = __builtin_amdgcn_mfma_f32_32x32x16_bf16(pa0, PK(l4, h4), o[1], 0, 0, 0);
;   const s16x4 l9 = tr_read<v_rd_off(2, 1, 0)>(vb), h9 = tr_read<v_rd_off(2, 1, 1)>(vb);
;   asm volatile("s_waitcnt lgkmcnt(8)" ::: "memory"); SBAR();
;   o[1] = __builtin_amdgcn_mfma_f32_32x32x16_bf16(pa1, PK(l5, h5), o[1], 0, 0, 0);
;   const s16x4 l10 = tr_read<v_rd_off(2, 2, 0)>(vb), h10 = tr_read<v_rd_off(2, 2, 1)>(vb);
;   asm volatile("s_waitcnt lgkmcnt(8)" ::: "memory"); SBAR();
;   o[1] = __builtin_amdgcn_mfma_f32_32x32x16_bf16(pa2, PK(l6, h6), o[1], 0, 0, 0);
;   const s16x4 l11 = tr_read<v_rd_off(2, 3, 0)>(vb), h11 = tr_read<v_rd_off(2, 3, 1)>(vb);
;   asm volatile("s_waitcnt lgkmcnt(8)" ::: "memory"); SBAR();
;   o[1] = __builtin_amdgcn_mfma_f32_32x32x16_bf16(pa3, PK(l7, h7), o[1], 0, 0, 0);
	v_mfma_f32_32x32x16_bf16 v[82:97], v[242:245], v[246:249], v[82:97]
	v_mfma_f32_32x32x16_bf16 v[114:129], v[234:237], v[250:253], v[114:129]
	v_mfma_f32_32x32x16_bf16 v[82:97], v[238:241], v[250:253], v[82:97]
	v_exp_f32_e32 v66, v66
	v_exp_f32_e32 v67, v67
	v_exp_f32_e32 v68, v68
	v_exp_f32_e32 v69, v69
	v_exp_f32_e32 v70, v70
	v_exp_f32_e32 v71, v71
	v_exp_f32_e32 v72, v72
	v_exp_f32_e32 v73, v73
	v_add_f32_e32 v166, v168, v176
	v_add_f32_e32 v179, v175, v178
	v_add_f32_e32 v180, v169, v167
	v_add_f32_e32 v181, v174, v177
	v_exp_f32_e32 v74, v74
	v_exp_f32_e32 v75, v75
	v_exp_f32_e32 v76, v76
	v_exp_f32_e32 v77, v77
	v_add_f32_e32 v166, v170, v166
	v_add_f32_e32 v179, v173, v179
	v_add_f32_e32 v180, v165, v180
	v_add_f32_e32 v181, v171, v181
	v_exp_f32_e32 v78, v78
	v_exp_f32_e32 v79, v79
	v_exp_f32_e32 v80, v80
	v_exp_f32_e32 v81, v81
	v_add_f32_e32 v166, v163, v166
	v_add_f32_e32 v179, v172, v179
	v_add_f32_e32 v180, v162, v180
	v_add_f32_e32 v181, v164, v181
	v_add_f32_e32 v166, v66, v166
	v_add_f32_e32 v179, v67, v179
	v_add_f32_e32 v180, v68, v180
	v_add_f32_e32 v181, v69, v181
	v_add_f32_e32 v166, v70, v166
	v_add_f32_e32 v179, v71, v179
	v_add_f32_e32 v180, v72, v180
	v_add_f32_e32 v181, v73, v181
	v_add_f32_e32 v166, v74, v166
	v_add_f32_e32 v179, v75, v179
	v_add_f32_e32 v180, v76, v180
	v_add_f32_e32 v181, v77, v181
	v_add_f32_e32 v166, v78, v166
	v_add_f32_e32 v179, v79, v179
	v_add_f32_e32 v180, v80, v180
	v_add_f32_e32 v181, v81, v181
	v_add_f32_e32 v166, v166, v179
	v_add_f32_e32 v179, v180, v181
	v_add_f32_e32 v223, v166, v179
	v_mov_b32_e32 v224, v223
	v_cvt_pk_bf16_f32 v166, v176, v178
	v_cvt_pk_bf16_f32 v167, v167, v177
	v_cvt_pk_bf16_f32 v168, v168, v175
	s_nop 1
	v_permlane32_swap_b32_e32 v223, v224
	v_cvt_pk_bf16_f32 v169, v169, v174
	v_cvt_pk_bf16_f32 v170, v170, v173
	v_cvt_pk_bf16_f32 v171, v165, v171
	v_cvt_pk_bf16_f32 v172, v163, v172
	v_cvt_pk_bf16_f32 v173, v162, v164
	v_cvt_pk_bf16_f32 v174, v66, v67
	v_cvt_pk_bf16_f32 v175, v68, v69
	v_cvt_pk_bf16_f32 v176, v70, v71
	v_cvt_pk_bf16_f32 v177, v72, v73
	v_cvt_pk_bf16_f32 v178, v74, v75
	v_cvt_pk_bf16_f32 v179, v76, v77
	v_cvt_pk_bf16_f32 v180, v78, v79
	v_cvt_pk_bf16_f32 v181, v80, v81
	v_lshl_add_u64 v[190:191], s[42:43], 0, v[188:189]
	v_add_co_u32_e32 v70, vcc, s49, v190
	v_lshl_add_u64 v[196:197], s[42:43], 0, v[186:187]
	s_nop 0
	v_addc_co_u32_e32 v71, vcc, 0, v191, vcc
	v_add_co_u32_e32 v74, vcc, s28, v190
	s_nop 1
	v_addc_co_u32_e32 v75, vcc, 0, v191, vcc
	global_load_dwordx4 v[66:69], v[70:71], off offset:256
	s_nop 0
	global_load_dwordx4 v[70:73], v[70:71], off
	s_nop 0
	global_load_dwordx4 v[78:81], v[74:75], off offset:256
	s_nop 0
	global_load_dwordx4 v[74:77], v[74:75], off
	v_add_co_u32_e32 v162, vcc, s68, v196
	s_nop 1
	v_addc_co_u32_e32 v163, vcc, 0, v197, vcc
	global_load_dwordx4 v[162:165], v[162:163], off
	ds_read_b64_tr_b16 v[230:231], v201 offset:0
	ds_read_b64_tr_b16 v[232:233], v201 offset:0x800
	ds_read_b64_tr_b16 v[234:235], v201 offset:0x1000
	ds_read_b64_tr_b16 v[236:237], v201 offset:0x1800
	ds_read_b64_tr_b16 v[238:239], v201 offset:0x2000
	ds_read_b64_tr_b16 v[240:241], v201 offset:0x2800
	ds_read_b64_tr_b16 v[242:243], v201 offset:0x3000
	ds_read_b64_tr_b16 v[244:245], v201 offset:0x3800
	ds_read_b64_tr_b16 v[246:247], v201 offset:0x200
	ds_read_b64_tr_b16 v[248:249], v201 offset:0xa00
	s_waitcnt lgkmcnt(8)
	s_nop 0
	v_mfma_f32_32x32x16_bf16 v[2:17], v[166:169], v[230:233], v[2:17]
	ds_read_b64_tr_b16 v[230:231], v201 offset:0x1200
	ds_read_b64_tr_b16 v[232:233], v201 offset:0x1a00
	s_waitcnt lgkmcnt(8)
	v_mfma_f32_32x32x16_bf16 v[2:17], v[170:173], v[234:237], v[2:17]
	ds_read_b64_tr_b16 v[234:235], v201 offset:0x2200
	ds_read_b64_tr_b16 v[236:237], v201 offset:0x2a00
	s_waitcnt lgkmcnt(8)
	v_mfma_f32_32x32x16_bf16 v[2:17], v[174:177], v[238:241], v[2:17]
	ds_read_b64_tr_b16 v[238:239], v201 offset:0x3200
	ds_read_b64_tr_b16 v[240:241], v201 offset:0x3a00
	s_waitcnt lgkmcnt(8)
	v_mfma_f32_32x32x16_bf16 v[2:17], v[178:181], v[242:245], v[2:17]
	ds_read_b64_tr_b16 v[242:243], v201 offset:0x400
	ds_read_b64_tr_b16 v[244:245], v201 offset:0xc00
	s_waitcnt lgkmcnt(8)
	v_mfma_f32_32x32x16_bf16 v[50:65], v[166:169], v[246:249], v[50:65]
	ds_read_b64_tr_b16 v[246:247], v201 offset:0x1400
	ds_read_b64_tr_b16 v[248:249], v201 offset:0x1c00
	s_waitcnt lgkmcnt(8)
	v_mfma_f32_32x32x16_bf16 v[50:65], v[170:173], v[230:233], v[50:65]
	ds_read_b64_tr_b16 v[230:231], v201 offset:0x2400
	ds_read_b64_tr_b16 v[232:233], v201 offset:0x2c00
	s_waitcnt lgkmcnt(8)
	v_mfma_f32_32x32x16_bf16 v[50:65], v[174:177], v[234:237], v[50:65]
	ds_read_b64_tr_b16 v[234:235], v201 offset:0x3400
	ds_read_b64_tr_b16 v[236:237], v201 offset:0x3c00
	s_waitcnt lgkmcnt(8)
	v_mfma_f32_32x32x16_bf16 v[50:65], v[178:181], v[238:241], v[50:65]
	ds_read_b64_tr_b16 v[238:239], v201 offset:0x600
	ds_read_b64_tr_b16 v[240:241], v201 offset:0xe00
	s_waitcnt lgkmcnt(8)
	v_mfma_f32_32x32x16_bf16 v[34:49], v[166:169], v[242:245], v[34:49]
	ds_read_b64_tr_b16 v[242:243], v201 offset:0x1600
	ds_read_b64_tr_b16 v[244:245], v201 offset:0x1e00
	s_waitcnt lgkmcnt(8)
	v_mfma_f32_32x32x16_bf16 v[34:49], v[170:173], v[246:249], v[34:49]
	ds_read_b64_tr_b16 v[246:247], v201 offset:0x2600
	ds_read_b64_tr_b16 v[248:249], v201 offset:0x2e00
	s_waitcnt lgkmcnt(8)
	v_mfma_f32_32x32x16_bf16 v[34:49], v[174:177], v[230:233], v[34:49]
	ds_read_b64_tr_b16 v[230:231], v201 offset:0x3600
	ds_read_b64_tr_b16 v[232:233], v201 offset:0x3e00
	s_waitcnt lgkmcnt(8)
	v_mfma_f32_32x32x16_bf16 v[34:49], v[178:181], v[234:237], v[34:49]
	s_waitcnt lgkmcnt(6)
	v_mfma_f32_32x32x16_bf16 v[18:33], v[166:169], v[238:241], v[18:33]
	s_waitcnt lgkmcnt(4)
	v_mfma_f32_32x32x16_bf16 v[18:33], v[170:173], v[242:245], v[18:33]
	s_waitcnt lgkmcnt(2)
	v_mfma_f32_32x32x16_bf16 v[18:33], v[174:177], v[246:249], v[18:33]
	s_waitcnt lgkmcnt(0)
	v_max_f32_e32 v166, v114, v118
	v_max_f32_e32 v167, v115, v119
	v_max_f32_e32 v168, v117, v121
	v_max3_f32 v169, v116, v120, v124
	v_max3_f32 v168, v168, v125, v129
	v_max3_f32 v166, v166, v122, v126
	v_max3_f32 v167, v167, v123, v127
	v_max3_f32 v169, v169, v128, v84
	v_max3_f32 v168, v168, v85, v89
	v_max3_f32 v166, v166, v82, v86
	v_max3_f32 v167, v167, v83, v87
	v_max3_f32 v169, v169, v88, v92
	v_max3_f32 v168, v168, v93, v97
	v_mfma_f32_32x32x16_bf16 v[18:33], v[178:181], v[230:233], v[18:33]
	v_max3_f32 v166, v166, v90, v94
	v_max3_f32 v167, v167, v91, v95
	v_max3_f32 v168, v169, v96, v168
	v_max3_f32 v166, v166, v167, v168
	v_mov_b32_e32 v167, v166
	s_nop 1
	v_permlane32_swap_b32_e32 v166, v167
	v_max_f32_e32 v166, v166, v167
	v_cmp_ge_f32_e32 vcc, s48, v166
	s_cmp_eq_u64 vcc, exec
	s_cbranch_scc0 .LBB0_400
	v_mov_b32_e32 v227, v225
	v_mov_b32_e32 v226, 1.0

; __device__ __forceinline__ void qkt12_roll(f32x16& p0, f32x16& p1, const f32x16& negm, int kb, int qa, const bf16x8* qr) {
;   const int a0 = kb ^ (0 << 5); const bf16x8 x0 = lds_rd128<0>(a0), y0 = lds_rd128<12288>(a0);
;   const int a1 = kb ^ (1 << 5); const bf16x8 x1 = lds_rd128<0>(a1), y1 = lds_rd128<12288>(a1);
;   asm volatile("s_waitcnt lgkmcnt(2)" ::: "memory"); SBAR();
;   p0 = __builtin_amdgcn_mfma_f32_32x32x16_bf16(x0, qr[0], negm, 0, 0, 0); p1 = __builtin_amdgcn_mfma_f32_32x32x16_bf16(y0, qr[0], negm, 0, 0, 0);
;   const int a2 = kb ^ (2 << 5); const bf16x8 x2 = lds_rd128<0>(a2), y2 = lds_rd128<12288>(a2);
;   asm volatile("s_waitcnt lgkmcnt(2)" ::: "memory"); SBAR();
;   p0 = __builtin_amdgcn_mfma_f32_32x32x16_bf16(x1, qr[1], p0, 0, 0, 0); p1 = __builtin_amdgcn_mfma_f32_32x32x16_bf16(y1, qr[1], p1, 0, 0, 0);
;   const int a3 = kb ^ (3 << 5); const bf16x8 x3 = lds_rd128<0>(a3), y3 = lds_rd128<12288>(a3);
;   asm volatile("s_waitcnt lgkmcnt(2)" ::: "memory"); SBAR();
;   p0 = __builtin_amdgcn_mfma_f32_32x32x16_bf16(x2, qr[2], p0, 0, 0, 0); p1 = __builtin_amdgcn_mfma_f32_32x32x16_bf16(y2, qr[2], p1, 0, 0, 0);
;   const int a4 = kb ^ (0 << 5); const bf16x8 x4 = lds_rd128<128>(a4), y4 = lds_rd128<12416>(a4);
;   asm volatile("s_waitcnt lgkmcnt(2)" ::: "memory"); SBAR();
;   p0 = __builtin_amdgcn_mfma_f32_32x32x16_bf16(x3, qr[3], p0, 0, 0, 0); p1 = __builtin_amdgcn_mfma_f32_32x32x16_bf16(y3, qr[3], p1, 0, 0, 0);
;   const int a5 = kb ^ (1 << 5); const bf16x8 x5 = lds_rd128<128>(a5), y5 = lds_rd128<12416>(a5);
;   asm volatile("s_waitcnt lgkmcnt(2)" ::: "memory"); SBAR();
;   p0 = __builtin_amdgcn_mfma_f32_32x32x16_bf16(x4, qr[4], p0, 0, 0, 0); p1 = __builtin_amdgcn_mfma_f32_32x32x16_bf16(y4, qr[4], p1, 0, 0, 0);
;   const int a6 = kb ^ (2 << 5); const bf16x8 x6 = lds_rd128<128>(a6), y6 = lds_rd128<12416>(a6);
;   asm volatile("s_waitcnt lgkmcnt(2)" ::: "memory"); SBAR();
;   p0 = __builtin_amdgcn_mfma_f32_32x32x16_bf16(x5, qr[5], p0, 0, 0, 0); p1 = __builtin_amdgcn_mfma_f32_32x32x16_bf16(y5, qr[5], p1, 0, 0, 0);
;   const int a7 = kb ^ (3 << 5); const bf16x8 x7 = lds_rd128<128>(a7), y7 = lds_rd128<12416>(a7);
;   asm volatile("s_waitcnt lgkmcnt(2)" ::: "memory"); SBAR();
;   p0 = __builtin_amdgcn_mfma_f32_32x32x16_bf16(x6, qr[6], p0, 0, 0, 0); p1 = __builtin_amdgcn_mfma_f32_32x32x16_bf16(y6, qr[6], p1, 0, 0, 0);
.LBB0_392:
	v_xor_b32_e32 v66, 0x80000000, v225
	v_cndmask_b32_e64 v228, v66, v228, s[6:7]
	v_exp_f32_e32 v166, v114
	v_exp_f32_e32 v167, v116
	v_exp_f32_e32 v165, v124
	v_exp_f32_e32 v163, v126
	v_exp_f32_e32 v162, v128
	v_exp_f32_e32 v164, v129
	v_cmp_neq_f32_e64 s[6:7], v228, -v227
	s_cmp_eq_u64 s[6:7], 0
	s_cselect_b64 s[6:7], -1, 0
	v_cndmask_b32_e64 v113, -v227, v113, s[6:7]
	v_cndmask_b32_e64 v112, -v227, v112, s[6:7]
	v_cndmask_b32_e64 v111, -v227, v111, s[6:7]
	v_cndmask_b32_e64 v110, -v227, v110, s[6:7]
	v_cndmask_b32_e64 v109, -v227, v109, s[6:7]
	v_cndmask_b32_e64 v108, -v227, v108, s[6:7]
	v_cndmask_b32_e64 v107, -v227, v107, s[6:7]
	v_cndmask_b32_e64 v106, -v227, v106, s[6:7]
	v_cndmask_b32_e64 v105, -v227, v105, s[6:7]
	v_cndmask_b32_e64 v104, -v227, v104, s[6:7]
	v_cndmask_b32_e64 v103, -v227, v103, s[6:7]
	v_cndmask_b32_e64 v102, -v227, v102, s[6:7]
	v_cndmask_b32_e64 v101, -v227, v101, s[6:7]
	v_cndmask_b32_e64 v100, -v227, v100, s[6:7]
	v_cndmask_b32_e64 v99, -v227, v99, s[6:7]
	v_cndmask_b32_e64 v98, -v227, v98, s[6:7]
	v_exp_f32_e32 v177, v115
	v_exp_f32_e32 v176, v117
	v_exp_f32_e32 v168, v118
	v_exp_f32_e32 v175, v119
	v_exp_f32_e32 v169, v120
	v_exp_f32_e32 v174, v121
	v_exp_f32_e32 v170, v122
	v_exp_f32_e32 v173, v123
	v_exp_f32_e32 v171, v125
	v_exp_f32_e32 v172, v127
	s_waitcnt lgkmcnt(0)
	s_barrier
	ds_read_b128 v[66:69], v209 offset:0
	ds_read_b128 v[178:181], v209 offset:0x3000
	ds_read_b128 v[230:233], v215 offset:0
	ds_read_b128 v[234:237], v215 offset:0x3000
	s_waitcnt lgkmcnt(2)
	s_nop 0
	v_mfma_f32_32x32x16_bf16 v[114:129], v[66:69], v[158:161], v[98:113]
	v_mfma_f32_32x32x16_bf16 v[66:81], v[178:181], v[158:161], v[98:113]
	ds_read_b128 v[178:181], v216 offset:0
	ds_read_b128 v[238:241], v216 offset:0x3000
	s_waitcnt lgkmcnt(2)
	v_mfma_f32_32x32x16_bf16 v[114:129], v[230:233], v[154:157], v[114:129]
	ds_read_b128 v[230:233], v217 offset:0
	v_mfma_f32_32x32x16_bf16 v[66:81], v[234:237], v[154:157], v[66:81]
	ds_read_b128 v[234:237], v217 offset:0x3000
	s_waitcnt lgkmcnt(2)
	v_mfma_f32_32x32x16_bf16 v[114:129], v[178:181], v[150:153], v[114:129]
	ds_read_b128 v[178:181], v209 offset:0x80
	v_mfma_f32_32x32x16_bf16 v[66:81], v[238:241], v[150:153], v[66:81]
	ds_read_b128 v[238:241], v209 offset:0x3080
	s_waitcnt lgkmcnt(2)
	v_mfma_f32_32x32x16_bf16 v[114:129], v[230:233], v[146:149], v[114:129]
	ds_read_b128 v[230:233], v215 offset:0x80
	v_mfma_f32_32x32x16_bf16 v[66:81], v[234:237], v[146:149], v[66:81]
	ds_read_b128 v[234:237], v215 offset:0x3080
	s_waitcnt lgkmcnt(2)
	v_mfma_f32_32x32x16_bf16 v[114:129], v[178:181], v[142:145], v[114:129]
	ds_read_b128 v[178:181], v216 offset:0x80
	v_mfma_f32_32x32x16_bf16 v[66:81], v[238:241], v[142:145], v[66:81]
	ds_read_b128 v[238:241], v216 offset:0x3080
	s_waitcnt lgkmcnt(2)
	v_mfma_f32_32x32x16_bf16 v[114:129], v[230:233], v[138:141], v[114:129]
	ds_read_b128 v[230:233], v217 offset:0x80
	v_mfma_f32_32x32x16_bf16 v[66:81], v[234:237], v[138:141], v[66:81]
	ds_read_b128 v[234:237], v217 offset:0x3080
	s_waitcnt lgkmcnt(2)
	v_mfma_f32_32x32x16_bf16 v[114:129], v[178:181], v[134:137], v[114:129]
	ds_read_b128 v[178:181], v209 offset:0x100
	v_mfma_f32_32x32x16_bf16 v[66:81], v[238:241], v[134:137], v[66:81]
	ds_read_b128 v[238:241], v209 offset:0x3100
	ds_read_b128 v[242:245], v199 offset:0
	s_waitcnt lgkmcnt(3)
	v_mfma_f32_32x32x16_bf16 v[114:129], v[230:233], v[130:133], v[114:129]
	ds_read_b128 v[230:233], v215 offset:0x100
	v_mfma_f32_32x32x16_bf16 v[66:81], v[234:237], v[130:133], v[66:81]
	ds_read_b128 v[234:237], v215 offset:0x3100
	ds_read_b128 v[246:249], v199 offset:0x400
	s_waitcnt lgkmcnt(3)
	v_mfma_f32_32x32x16_bf16 v[114:129], v[178:181], v[242:245], v[114:129]
	ds_read_b128 v[178:181], v216 offset:0x100
	v_mfma_f32_32x32x16_bf16 v[66:81], v[238:241], v[242:245], v[66:81]
	ds_read_b128 v[238:241], v216 offset:0x3100
	ds_read_b128 v[242:245], v199 offset:0x800
	s_waitcnt lgkmcnt(3)
	v_mfma_f32_32x32x16_bf16 v[114:129], v[230:233], v[246:249], v[114:129]
	ds_read_b128 v[230:233], v217 offset:0x100
	v_mfma_f32_32x32x16_bf16 v[66:81], v[234:237], v[246:249], v[66:81]
	ds_read_b128 v[234:237], v217 offset:0x3100
	ds_read_b128 v[246:249], v199 offset:0xc00
	s_waitcnt lgkmcnt(3)
	v_mfma_f32_32x32x16_bf16 v[114:129], v[178:181], v[242:245], v[114:129]
	s_waitcnt lgkmcnt(0)
; __device__ __forceinline__ void pv_d0(f32x16* o, int vb, bf16x8 pa0, bf16x8 pa1, bf16x8 pa2, bf16x8 pa3) {
;     ...
;   const s16x4 l0 = tr_read<v_rd_off(0, 0, 0)>(vb), h0 = tr_read<v_rd_off(0, 0, 1)>(vb);
;   const s16x4 l1 = tr_read<v_rd_off(0, 1, 0)>(vb), h1 = tr_read<v_rd_off(0, 1, 1)>(vb);
;   const s16x4 l2 = tr_read<v_rd_off(0, 2, 0)>(vb), h2 = tr_read<v_rd_off(0, 2, 1)>(vb);
;   const s16x4 l3 = tr_read<v_rd_off(0, 3, 0)>(vb), h3 = tr_read<v_rd_off(0, 3, 1)>(vb);
;   const s16x4 l4 = tr_read<v_rd_off(1, 0, 0)>(vb), h4 = tr_read<v_rd_off(1, 0, 1)>(vb);
;   asm volatile("s_waitcnt lgkmcnt(8)" ::: "memory"); SBAR();
;   o[0] = __builtin_amdgcn_mfma_f32_32x32x16_bf16(pa0, PK(l0, h0), o[0], 0, 0, 0);
;   const s16x4 l5 = tr_read<v_rd_off(1, 1, 0)>(vb), h5 = tr_read<v_rd_off(1, 1, 1)>(vb);
;   asm volatile("s_waitcnt lgkmcnt(8)" ::: "memory"); SBAR();
;   o[0] = __builtin_amdgcn_mfma_f32_32x32x16_bf16(pa1, PK(l1, h1), o[0], 0, 0, 0);
;   const s16x4 l6 = tr_read<v_rd_off(1, 2, 0)>(vb), h6 = tr_read<v_rd_off(1, 2, 1)>(vb);
;   asm volatile("s_waitcnt lgkmcnt(8)" ::: "memory"); SBAR();
;   o[0] = __builtin_amdgcn_mfma_f32_32x32x16_bf16(pa2, PK(l2, h2), o[0], 0, 0, 0);
;   const s16x4 l7 = tr_read<v_rd_off(1, 3, 0)>(vb), h7 = tr_read<v_rd_off(1, 3, 1)>(vb);
;   asm volatile("s_waitcnt lgkmcnt(8)" ::: "memory"); SBAR();
;   o[0] = __builtin_amdgcn_mfma_f32_32x32x16_bf16(pa3, PK(l3, h3), o[0], 0, 0, 0);
;   const s16x4 l8 = tr_read<v_rd_off(2, 0, 0)>(vb), h8 = tr_read<v_rd_off(2, 0, 1)>(vb);
;   asm volatile("s_waitcnt lgkmcnt(8)" ::: "memory"); SBAR();
;   o[1] = __builtin_amdgcn_mfma_f32_32x32x16_bf16(pa0, PK(l4, h4), o[1], 0, 0, 0);
;   const s16x4 l9 = tr_read<v_rd_off(2, 1, 0)>(vb), h9 = tr_read<v_rd_off(2, 1, 1)>(vb);
;   asm volatile("s_waitcnt lgkmcnt(8)" ::: "memory"); SBAR();
;   o[1] = __builtin_amdgcn_mfma_f32_32x32x16_bf16(pa1, PK(l5, h5), o[1], 0, 0, 0);
;   const s16x4 l10 = tr_read<v_rd_off(2, 2, 0)>(vb), h10 = tr_read<v_rd_off(2, 2, 1)>(vb);
;   asm volatile("s_waitcnt lgkmcnt(8)" ::: "memory"); SBAR();
;   o[1] = __builtin_amdgcn_mfma_f32_32x32x16_bf16(pa2, PK(l6, h6), o[1], 0, 0, 0);
;   const s16x4 l11 = tr_read<v_rd_off(2, 3, 0)>(vb), h11 = tr_read<v_rd_off(2, 3, 1)>(vb);
;   asm volatile("s_waitcnt lgkmcnt(8)" ::: "memory"); SBAR();
;   o[1] = __builtin_amdgcn_mfma_f32_32x32x16_bf16(pa3, PK(l7, h7), o[1], 0, 0, 0);
	v_mfma_f32_32x32x16_bf16 v[66:81], v[238:241], v[242:245], v[66:81]
	v_mfma_f32_32x32x16_bf16 v[114:129], v[230:233], v[246:249], v[114:129]
	v_mfma_f32_32x32x16_bf16 v[66:81], v[234:237], v[246:249], v[66:81]
	v_exp_f32_e32 v82, v82
	v_exp_f32_e32 v83, v83
	v_exp_f32_e32 v84, v84
	v_exp_f32_e32 v85, v85
	v_exp_f32_e32 v86, v86
	v_exp_f32_e32 v87, v87
	v_exp_f32_e32 v88, v88
	v_exp_f32_e32 v89, v89
	v_add_f32_e32 v178, v168, v166
	v_add_f32_e32 v179, v175, v177
	v_add_f32_e32 v180, v169, v167
	v_add_f32_e32 v181, v174, v176
	v_exp_f32_e32 v90, v90
	v_exp_f32_e32 v91, v91
	v_exp_f32_e32 v92, v92
	v_exp_f32_e32 v93, v93
	v_add_f32_e32 v178, v170, v178
	v_add_f32_e32 v179, v173, v179
	v_add_f32_e32 v180, v165, v180
	v_add_f32_e32 v181, v171, v181
	v_exp_f32_e32 v94, v94
	v_exp_f32_e32 v95, v95
	v_exp_f32_e32 v96, v96
	v_exp_f32_e32 v97, v97
	v_add_f32_e32 v178, v163, v178
	v_add_f32_e32 v179, v172, v179
	v_add_f32_e32 v180, v162, v180
	v_add_f32_e32 v181, v164, v181
	v_add_f32_e32 v178, v82, v178
	v_add_f32_e32 v179, v179, v83
	v_add_f32_e32 v180, v180, v84
	v_add_f32_e32 v181, v181, v85
	v_add_f32_e32 v178, v86, v178
	v_add_f32_e32 v179, v87, v179
	v_add_f32_e32 v180, v88, v180
	v_add_f32_e32 v181, v89, v181
	v_add_f32_e32 v178, v90, v178
	v_add_f32_e32 v179, v91, v179
	v_add_f32_e32 v180, v92, v180
	v_add_f32_e32 v181, v93, v181
	v_add_f32_e32 v178, v94, v178
	v_add_f32_e32 v179, v95, v179
	v_add_f32_e32 v180, v96, v180
	v_add_f32_e32 v181, v97, v181
	v_add_f32_e32 v178, v178, v179
	v_add_f32_e32 v179, v180, v181
	v_add_f32_e32 v229, v178, v179
	v_mov_b32_e32 v230, v229
	v_cvt_pk_bf16_f32 v166, v166, v177
	v_cvt_pk_bf16_f32 v167, v167, v176
	v_cvt_pk_bf16_f32 v168, v168, v175
	v_cvt_pk_bf16_f32 v169, v169, v174
	s_nop 1
	v_permlane32_swap_b32_e32 v229, v230
	v_cvt_pk_bf16_f32 v170, v170, v173
	v_cvt_pk_bf16_f32 v171, v165, v171
	v_cvt_pk_bf16_f32 v172, v163, v172
	v_cvt_pk_bf16_f32 v173, v162, v164
	v_cvt_pk_bf16_f32 v174, v82, v83
	v_cvt_pk_bf16_f32 v175, v84, v85
	v_cvt_pk_bf16_f32 v176, v86, v87
	v_cvt_pk_bf16_f32 v177, v88, v89
	v_cvt_pk_bf16_f32 v178, v90, v91
	v_cvt_pk_bf16_f32 v179, v92, v93
	v_cvt_pk_bf16_f32 v180, v94, v95
	v_cvt_pk_bf16_f32 v181, v96, v97
	s_nop 0
	v_add_co_u32_e32 v86, vcc, s69, v190
	s_nop 1
	v_addc_co_u32_e32 v87, vcc, 0, v191, vcc
	v_add_co_u32_e32 v90, vcc, s74, v190
	s_nop 1
	v_addc_co_u32_e32 v91, vcc, 0, v191, vcc
	global_load_dwordx4 v[82:85], v[86:87], off offset:256
	s_nop 0
	global_load_dwordx4 v[86:89], v[86:87], off
	s_nop 0
	global_load_dwordx4 v[94:97], v[90:91], off offset:256
	s_nop 0
	global_load_dwordx4 v[90:93], v[90:91], off
	v_add_co_u32_e32 v162, vcc, s75, v196
	s_nop 1
	v_addc_co_u32_e32 v163, vcc, 0, v197, vcc
	global_load_dwordx4 v[162:165], v[162:163], off
	ds_read_b64_tr_b16 v[232:233], v208 offset:0
	ds_read_b64_tr_b16 v[234:235], v208 offset:0x800
	ds_read_b64_tr_b16 v[236:237], v208 offset:0x1000
	ds_read_b64_tr_b16 v[238:239], v208 offset:0x1800
	ds_read_b64_tr_b16 v[240:241], v208 offset:0x2000
	ds_read_b64_tr_b16 v[242:243], v208 offset:0x2800
	ds_read_b64_tr_b16 v[244:245], v208 offset:0x3000
	ds_read_b64_tr_b16 v[246:247], v208 offset:0x3800
	ds_read_b64_tr_b16 v[248:249], v208 offset:0x200
	ds_read_b64_tr_b16 v[250:251], v208 offset:0xa00
	s_waitcnt lgkmcnt(8)
	s_nop 0
	v_mfma_f32_32x32x16_bf16 v[2:17], v[166:169], v[232:235], v[2:17]
	ds_read_b64_tr_b16 v[232:233], v208 offset:0x1200
	ds_read_b64_tr_b16 v[234:235], v208 offset:0x1a00
	s_waitcnt lgkmcnt(8)
	v_mfma_f32_32x32x16_bf16 v[2:17], v[170:173], v[236:239], v[2:17]
	ds_read_b64_tr_b16 v[236:237], v208 offset:0x2200
	ds_read_b64_tr_b16 v[238:239], v208 offset:0x2a00
	s_waitcnt lgkmcnt(8)
	v_mfma_f32_32x32x16_bf16 v[2:17], v[174:177], v[240:243], v[2:17]
	ds_read_b64_tr_b16 v[240:241], v208 offset:0x3200
	ds_read_b64_tr_b16 v[242:243], v208 offset:0x3a00
	s_waitcnt lgkmcnt(8)
	v_mfma_f32_32x32x16_bf16 v[2:17], v[178:181], v[244:247], v[2:17]
	ds_read_b64_tr_b16 v[244:245], v208 offset:0x400
	ds_read_b64_tr_b16 v[246:247], v208 offset:0xc00
	s_waitcnt lgkmcnt(8)
	v_mfma_f32_32x32x16_bf16 v[50:65], v[166:169], v[248:251], v[50:65]
	ds_read_b64_tr_b16 v[248:249], v208 offset:0x1400
	ds_read_b64_tr_b16 v[250:251], v208 offset:0x1c00
	s_waitcnt lgkmcnt(8)
	v_mfma_f32_32x32x16_bf16 v[50:65], v[170:173], v[232:235], v[50:65]
	ds_read_b64_tr_b16 v[232:233], v208 offset:0x2400
	ds_read_b64_tr_b16 v[234:235], v208 offset:0x2c00
	s_waitcnt lgkmcnt(8)
	v_mfma_f32_32x32x16_bf16 v[50:65], v[174:177], v[236:239], v[50:65]
	ds_read_b64_tr_b16 v[236:237], v208 offset:0x3400
	ds_read_b64_tr_b16 v[238:239], v208 offset:0x3c00
	s_waitcnt lgkmcnt(8)
	v_mfma_f32_32x32x16_bf16 v[50:65], v[178:181], v[240:243], v[50:65]
	ds_read_b64_tr_b16 v[240:241], v208 offset:0x600
	ds_read_b64_tr_b16 v[242:243], v208 offset:0xe00
	s_waitcnt lgkmcnt(8)
	v_mfma_f32_32x32x16_bf16 v[34:49], v[166:169], v[244:247], v[34:49]
	ds_read_b64_tr_b16 v[244:245], v208 offset:0x1600
	ds_read_b64_tr_b16 v[246:247], v208 offset:0x1e00
	s_waitcnt lgkmcnt(8)
	v_mfma_f32_32x32x16_bf16 v[34:49], v[170:173], v[248:251], v[34:49]
	ds_read_b64_tr_b16 v[248:249], v208 offset:0x2600
	ds_read_b64_tr_b16 v[250:251], v208 offset:0x2e00
	s_waitcnt lgkmcnt(8)
	v_mfma_f32_32x32x16_bf16 v[34:49], v[174:177], v[232:235], v[34:49]
	ds_read_b64_tr_b16 v[232:233], v208 offset:0x3600
	ds_read_b64_tr_b16 v[234:235], v208 offset:0x3e00
	s_waitcnt lgkmcnt(8)
	v_mfma_f32_32x32x16_bf16 v[34:49], v[178:181], v[236:239], v[34:49]
	s_waitcnt lgkmcnt(6)
	v_mfma_f32_32x32x16_bf16 v[18:33], v[166:169], v[240:243], v[18:33]
	s_waitcnt lgkmcnt(4)
	v_mfma_f32_32x32x16_bf16 v[18:33], v[170:173], v[244:247], v[18:33]
	s_waitcnt lgkmcnt(2)
	v_mfma_f32_32x32x16_bf16 v[18:33], v[174:177], v[248:251], v[18:33]
	s_waitcnt lgkmcnt(0)
	v_max_f32_e32 v166, v114, v118
	v_max_f32_e32 v167, v115, v119
	v_max_f32_e32 v168, v117, v121
	v_max3_f32 v169, v116, v120, v124
	v_max3_f32 v168, v168, v125, v129
	v_max3_f32 v166, v166, v122, v126
	v_max3_f32 v167, v167, v123, v127
	v_max3_f32 v169, v169, v128, v68
	v_max3_f32 v168, v168, v69, v73
	v_max3_f32 v166, v166, v66, v70
	v_max3_f32 v167, v167, v67, v71
	v_max3_f32 v169, v169, v72, v76
	v_max3_f32 v168, v168, v77, v81
	v_mfma_f32_32x32x16_bf16 v[18:33], v[178:181], v[232:235], v[18:33]
	v_max3_f32 v166, v166, v74, v78
	v_max3_f32 v167, v167, v75, v79
	v_max3_f32 v168, v169, v80, v168
	v_max3_f32 v166, v166, v167, v168
	v_mov_b32_e32 v167, v166
	s_nop 1
	v_permlane32_swap_b32_e32 v166, v167
	v_max_f32_e32 v167, v166, v167
	v_cmp_ge_f32_e32 vcc, s48, v167
	s_cmp_eq_u64 vcc, exec
	v_mov_b32_e32 v166, 1.0
	s_cbranch_scc0 .LBB0_401
	v_mov_b32_e32 v225, v227

; __device__ __forceinline__ void qkt8_roll(f32x16& p0, f32x16& p1, const f32x16& negm, int kb, const bf16x8* qr) {
;   const int a0 = kb ^ (0 << 5); const bf16x8 x0 = lds_rd128<0>(a0), y0 = lds_rd128<8192>(a0);
;   const int a1 = kb ^ (1 << 5); const bf16x8 x1 = lds_rd128<0>(a1), y1 = lds_rd128<8192>(a1);
;   const int a2 = kb ^ (2 << 5); const bf16x8 x2 = lds_rd128<0>(a2), y2 = lds_rd128<8192>(a2);
;   asm volatile("s_waitcnt lgkmcnt(4)" ::: "memory"); SBAR_M();
;   p0 = __builtin_amdgcn_mfma_f32_32x32x16_bf16(x0, qr[0], negm, 0, 0, 0); p1 = __builtin_amdgcn_mfma_f32_32x32x16_bf16(y0, qr[0], negm, 0, 0, 0);
;   const int a3 = kb ^ (3 << 5); const bf16x8 x3 = lds_rd128<0>(a3), y3 = lds_rd128<8192>(a3);
;   asm volatile("s_waitcnt lgkmcnt(4)" ::: "memory"); SBAR_M();
;   p0 = __builtin_amdgcn_mfma_f32_32x32x16_bf16(x1, qr[1], p0, 0, 0, 0); p1 = __builtin_amdgcn_mfma_f32_32x32x16_bf16(y1, qr[1], p1, 0, 0, 0);
;   const int a4 = kb ^ (4 << 5); const bf16x8 x4 = lds_rd128<0>(a4), y4 = lds_rd128<8192>(a4);
;   asm volatile("s_waitcnt lgkmcnt(4)" ::: "memory"); SBAR_M();
;   p0 = __builtin_amdgcn_mfma_f32_32x32x16_bf16(x2, qr[2], p0, 0, 0, 0); p1 = __builtin_amdgcn_mfma_f32_32x32x16_bf16(y2, qr[2], p1, 0, 0, 0);
;   const int a5 = kb ^ (5 << 5); const bf16x8 x5 = lds_rd128<0>(a5), y5 = lds_rd128<8192>(a5);
;   asm volatile("s_waitcnt lgkmcnt(4)" ::: "memory"); SBAR_M();
;   p0 = __builtin_amdgcn_mfma_f32_32x32x16_bf16(x3, qr[3], p0, 0, 0, 0); p1 = __builtin_amdgcn_mfma_f32_32x32x16_bf16(y3, qr[3], p1, 0, 0, 0);
;   const int a6 = kb ^ (6 << 5); const bf16x8 x6 = lds_rd128<0>(a6), y6 = lds_rd128<8192>(a6);
;   asm volatile("s_waitcnt lgkmcnt(4)" ::: "memory"); SBAR_M();
;   p0 = __builtin_amdgcn_mfma_f32_32x32x16_bf16(x4, qr[4], p0, 0, 0, 0); p1 = __builtin_amdgcn_mfma_f32_32x32x16_bf16(y4, qr[4], p1, 0, 0, 0);
;   const int a7 = kb ^ (7 << 5); const bf16x8 x7 = lds_rd128<0>(a7), y7 = lds_rd128<8192>(a7);
;   asm volatile("s_waitcnt lgkmcnt(4)" ::: "memory"); SBAR_M();
;   p0 = __builtin_amdgcn_mfma_f32_32x32x16_bf16(x5, qr[5], p0, 0, 0, 0); p1 = __builtin_amdgcn_mfma_f32_32x32x16_bf16(y5, qr[5], p1, 0, 0, 0);
;   asm volatile("s_waitcnt lgkmcnt(2)" ::: "memory"); SBAR_M();
;   p0 = __builtin_amdgcn_mfma_f32_32x32x16_bf16(x6, qr[6], p0, 0, 0, 0); p1 = __builtin_amdgcn_mfma_f32_32x32x16_bf16(y6, qr[6], p1, 0, 0, 0);
.LBB0_421:
	v_exp_f32_e32 v66, v66
	v_exp_f32_e32 v67, v67
	v_exp_f32_e32 v68, v68
	v_exp_f32_e32 v69, v69
	v_exp_f32_e32 v70, v70
	v_exp_f32_e32 v71, v71
	v_exp_f32_e32 v72, v72
	v_exp_f32_e32 v73, v73
	v_add_f32_e32 v98, v148, v146
	v_add_f32_e32 v99, v159, v161
	v_add_f32_e32 v100, v149, v147
	v_add_f32_e32 v101, v158, v160
	v_exp_f32_e32 v74, v74
	v_exp_f32_e32 v75, v75
	v_exp_f32_e32 v76, v76
	v_exp_f32_e32 v77, v77
	v_add_f32_e32 v98, v150, v98
	v_add_f32_e32 v99, v157, v99
	v_add_f32_e32 v100, v151, v100
	v_add_f32_e32 v101, v156, v101
	v_exp_f32_e32 v78, v78
	v_exp_f32_e32 v79, v79
	v_exp_f32_e32 v80, v80
	v_exp_f32_e32 v81, v81
	v_add_f32_e32 v98, v152, v98
	v_add_f32_e32 v99, v155, v99
	v_add_f32_e32 v100, v153, v100
	v_add_f32_e32 v101, v154, v101
	v_add_f32_e32 v98, v66, v98
	v_add_f32_e32 v99, v67, v99
	v_add_f32_e32 v100, v68, v100
	v_add_f32_e32 v101, v69, v101
	v_add_f32_e32 v98, v70, v98
	v_add_f32_e32 v99, v71, v99
	v_add_f32_e32 v100, v72, v100
	v_add_f32_e32 v101, v73, v101
	v_add_f32_e32 v98, v74, v98
	v_add_f32_e32 v99, v75, v99
	v_add_f32_e32 v100, v76, v100
	v_add_f32_e32 v101, v77, v101
	v_add_f32_e32 v98, v78, v98
	v_add_f32_e32 v99, v79, v99
	v_add_f32_e32 v100, v80, v100
	v_add_f32_e32 v101, v81, v101
	v_add_f32_e32 v98, v98, v99
	v_add_f32_e32 v99, v100, v101
	v_add_f32_e32 v228, v98, v99
	v_mov_b32_e32 v229, v228
	v_cvt_pk_bf16_f32 v146, v146, v161
	v_cvt_pk_bf16_f32 v147, v147, v160
	v_cvt_pk_bf16_f32 v148, v148, v159
	v_cvt_pk_bf16_f32 v149, v149, v158
	v_cvt_pk_bf16_f32 v150, v150, v157
	v_cvt_pk_bf16_f32 v151, v151, v156
	v_cvt_pk_bf16_f32 v152, v152, v155
	v_cvt_pk_bf16_f32 v153, v153, v154
	v_cvt_pk_bf16_f32 v158, v66, v67
	v_cvt_pk_bf16_f32 v159, v68, v69
	v_cvt_pk_bf16_f32 v160, v70, v71
	v_cvt_pk_bf16_f32 v161, v72, v73
	v_cvt_pk_bf16_f32 v154, v74, v75
	v_cvt_pk_bf16_f32 v155, v76, v77
	v_cvt_pk_bf16_f32 v156, v78, v79
	v_cvt_pk_bf16_f32 v157, v80, v81
	s_nop 1
	v_permlane32_swap_b32_e32 v228, v229
	v_cmp_neq_f32_e64 s[6:7], v232, -v227
	s_cmp_eq_u64 s[6:7], 0
	s_cselect_b64 s[6:7], -1, 0
	v_cndmask_b32_e64 v81, -v227, v97, s[6:7]
	v_cndmask_b32_e64 v80, -v227, v96, s[6:7]
	v_cndmask_b32_e64 v79, -v227, v95, s[6:7]
	v_cndmask_b32_e64 v78, -v227, v94, s[6:7]
	v_cndmask_b32_e64 v77, -v227, v93, s[6:7]
	v_cndmask_b32_e64 v76, -v227, v92, s[6:7]
	v_cndmask_b32_e64 v75, -v227, v91, s[6:7]
	v_cndmask_b32_e64 v74, -v227, v90, s[6:7]
	v_cndmask_b32_e64 v73, -v227, v89, s[6:7]
	v_cndmask_b32_e64 v72, -v227, v88, s[6:7]
	v_cndmask_b32_e64 v71, -v227, v87, s[6:7]
	v_cndmask_b32_e64 v70, -v227, v86, s[6:7]
	v_cndmask_b32_e64 v69, -v227, v85, s[6:7]
	v_cndmask_b32_e64 v68, -v227, v84, s[6:7]
	v_cndmask_b32_e64 v67, -v227, v83, s[6:7]
	v_cndmask_b32_e64 v66, -v227, v82, s[6:7]
	ds_read_b128 v[82:85], v224 offset:0
	ds_read_b128 v[162:165], v224 offset:0x2000
	ds_read_b128 v[166:169], v223 offset:0
	ds_read_b128 v[170:173], v223 offset:0x2000
	ds_read_b128 v[174:177], v222 offset:0
	ds_read_b128 v[188:191], v222 offset:0x2000
	s_waitcnt lgkmcnt(4)
	s_nop 1
	v_mfma_f32_32x32x16_bf16 v[98:113], v[82:85], v[142:145], v[66:81]
	v_mfma_f32_32x32x16_bf16 v[82:97], v[162:165], v[142:145], v[66:81]
	ds_read_b128 v[162:165], v221 offset:0
	ds_read_b128 v[192:195], v221 offset:0x2000
	s_waitcnt lgkmcnt(4)
	v_mfma_f32_32x32x16_bf16 v[98:113], v[166:169], v[138:141], v[98:113]
	ds_read_b128 v[166:169], v220 offset:0
	v_mfma_f32_32x32x16_bf16 v[82:97], v[170:173], v[138:141], v[82:97]
	ds_read_b128 v[170:173], v220 offset:0x2000
	s_waitcnt lgkmcnt(4)
	v_mfma_f32_32x32x16_bf16 v[98:113], v[174:177], v[134:137], v[98:113]
	ds_read_b128 v[174:177], v219 offset:0
	v_mfma_f32_32x32x16_bf16 v[82:97], v[188:191], v[134:137], v[82:97]
	ds_read_b128 v[188:191], v219 offset:0x2000
	s_waitcnt lgkmcnt(4)
	v_mfma_f32_32x32x16_bf16 v[98:113], v[162:165], v[130:133], v[98:113]
	ds_read_b128 v[162:165], v218 offset:0
	v_mfma_f32_32x32x16_bf16 v[82:97], v[192:195], v[130:133], v[82:97]
	ds_read_b128 v[192:195], v218 offset:0x2000
	s_waitcnt lgkmcnt(4)
	v_mfma_f32_32x32x16_bf16 v[98:113], v[166:169], v[126:129], v[98:113]
	ds_read_b128 v[166:169], v217 offset:0
	v_mfma_f32_32x32x16_bf16 v[82:97], v[170:173], v[126:129], v[82:97]
	ds_read_b128 v[170:173], v217 offset:0x2000
	s_waitcnt lgkmcnt(4)
	v_mfma_f32_32x32x16_bf16 v[98:113], v[174:177], v[122:125], v[98:113]
	s_waitcnt lgkmcnt(2)
	v_mfma_f32_32x32x16_bf16 v[82:97], v[188:191], v[122:125], v[82:97]
	v_mfma_f32_32x32x16_bf16 v[98:113], v[162:165], v[118:121], v[98:113]
	s_waitcnt lgkmcnt(0)
	v_mfma_f32_32x32x16_bf16 v[82:97], v[192:195], v[118:121], v[82:97]
	v_mfma_f32_32x32x16_bf16 v[98:113], v[166:169], v[114:117], v[98:113]
	v_mfma_f32_32x32x16_bf16 v[82:97], v[170:173], v[114:117], v[82:97]
	s_nop 10
	v_max_f32_e32 v162, v98, v102
	v_max_f32_e32 v163, v99, v103
	v_max_f32_e32 v164, v101, v105
	v_max3_f32 v165, v100, v104, v108
	v_max3_f32 v164, v164, v109, v113
	v_max3_f32 v162, v162, v106, v110
	v_max3_f32 v163, v163, v107, v111
	v_max3_f32 v165, v165, v112, v84
	v_max3_f32 v164, v164, v85, v89
	v_max3_f32 v162, v162, v82, v86
	v_max3_f32 v163, v163, v83, v87
	v_max3_f32 v165, v165, v88, v92
	v_max3_f32 v164, v164, v93, v97
	v_max3_f32 v162, v162, v90, v94
	v_max3_f32 v163, v163, v91, v95
	v_max3_f32 v164, v165, v96, v164
	v_max3_f32 v162, v162, v163, v164
	v_mov_b32_e32 v163, v162
	s_nop 1
	v_permlane32_swap_b32_e32 v162, v163
	v_max_f32_e32 v162, v162, v163
	v_cmp_ge_f32_e32 vcc, s48, v162
	s_cmp_eq_u64 vcc, exec
	s_cbranch_scc0 .LBB0_435
	v_mov_b32_e32 v231, v227
	v_mov_b32_e32 v230, 1.0

; __device__ __forceinline__ void qkt8_roll(f32x16& p0, f32x16& p1, const f32x16& negm, int kb, const bf16x8* qr) {
;   const int a0 = kb ^ (0 << 5); const bf16x8 x0 = lds_rd128<0>(a0), y0 = lds_rd128<8192>(a0);
;   const int a1 = kb ^ (1 << 5); const bf16x8 x1 = lds_rd128<0>(a1), y1 = lds_rd128<8192>(a1);
;   const int a2 = kb ^ (2 << 5); const bf16x8 x2 = lds_rd128<0>(a2), y2 = lds_rd128<8192>(a2);
;   asm volatile("s_waitcnt lgkmcnt(4)" ::: "memory"); SBAR_M();
;   p0 = __builtin_amdgcn_mfma_f32_32x32x16_bf16(x0, qr[0], negm, 0, 0, 0); p1 = __builtin_amdgcn_mfma_f32_32x32x16_bf16(y0, qr[0], negm, 0, 0, 0);
;   const int a3 = kb ^ (3 << 5); const bf16x8 x3 = lds_rd128<0>(a3), y3 = lds_rd128<8192>(a3);
;   asm volatile("s_waitcnt lgkmcnt(4)" ::: "memory"); SBAR_M();
;   p0 = __builtin_amdgcn_mfma_f32_32x32x16_bf16(x1, qr[1], p0, 0, 0, 0); p1 = __builtin_amdgcn_mfma_f32_32x32x16_bf16(y1, qr[1], p1, 0, 0, 0);
;   const int a4 = kb ^ (4 << 5); const bf16x8 x4 = lds_rd128<0>(a4), y4 = lds_rd128<8192>(a4);
;   asm volatile("s_waitcnt lgkmcnt(4)" ::: "memory"); SBAR_M();
;   p0 = __builtin_amdgcn_mfma_f32_32x32x16_bf16(x2, qr[2], p0, 0, 0, 0); p1 = __builtin_amdgcn_mfma_f32_32x32x16_bf16(y2, qr[2], p1, 0, 0, 0);
;   const int a5 = kb ^ (5 << 5); const bf16x8 x5 = lds_rd128<0>(a5), y5 = lds_rd128<8192>(a5);
;   asm volatile("s_waitcnt lgkmcnt(4)" ::: "memory"); SBAR_M();
;   p0 = __builtin_amdgcn_mfma_f32_32x32x16_bf16(x3, qr[3], p0, 0, 0, 0); p1 = __builtin_amdgcn_mfma_f32_32x32x16_bf16(y3, qr[3], p1, 0, 0, 0);
;   const int a6 = kb ^ (6 << 5); const bf16x8 x6 = lds_rd128<0>(a6), y6 = lds_rd128<8192>(a6);
;   asm volatile("s_waitcnt lgkmcnt(4)" ::: "memory"); SBAR_M();
;   p0 = __builtin_amdgcn_mfma_f32_32x32x16_bf16(x4, qr[4], p0, 0, 0, 0); p1 = __builtin_amdgcn_mfma_f32_32x32x16_bf16(y4, qr[4], p1, 0, 0, 0);
;   const int a7 = kb ^ (7 << 5); const bf16x8 x7 = lds_rd128<0>(a7), y7 = lds_rd128<8192>(a7);
;   asm volatile("s_waitcnt lgkmcnt(4)" ::: "memory"); SBAR_M();
;   p0 = __builtin_amdgcn_mfma_f32_32x32x16_bf16(x5, qr[5], p0, 0, 0, 0); p1 = __builtin_amdgcn_mfma_f32_32x32x16_bf16(y5, qr[5], p1, 0, 0, 0);
;   asm volatile("s_waitcnt lgkmcnt(2)" ::: "memory"); SBAR_M();
;   p0 = __builtin_amdgcn_mfma_f32_32x32x16_bf16(x6, qr[6], p0, 0, 0, 0); p1 = __builtin_amdgcn_mfma_f32_32x32x16_bf16(y6, qr[6], p1, 0, 0, 0);
.LBB0_427:
	v_exp_f32_e32 v146, v98
	v_exp_f32_e32 v153, v99
	v_exp_f32_e32 v147, v100
	v_exp_f32_e32 v152, v101
	v_exp_f32_e32 v148, v102
	v_exp_f32_e32 v151, v103
	v_exp_f32_e32 v149, v104
	v_exp_f32_e32 v150, v105
	v_exp_f32_e32 v103, v106
	v_exp_f32_e32 v105, v107
	v_exp_f32_e32 v101, v108
	v_exp_f32_e32 v104, v109
	v_exp_f32_e32 v99, v110
	v_exp_f32_e32 v102, v111
	v_exp_f32_e32 v98, v112
	v_exp_f32_e32 v100, v113
	v_xor_b32_e32 v106, 0x80000000, v227
	v_exp_f32_e32 v82, v82
	v_exp_f32_e32 v83, v83
	v_exp_f32_e32 v84, v84
	v_exp_f32_e32 v85, v85
	v_cndmask_b32_e64 v232, v106, v232, s[6:7]
	v_exp_f32_e32 v86, v86
	v_exp_f32_e32 v87, v87
	v_exp_f32_e32 v88, v88
	v_exp_f32_e32 v89, v89
	v_add_f32_e32 v106, v148, v146
	v_add_f32_e32 v107, v151, v153
	v_add_f32_e32 v108, v149, v147
	v_add_f32_e32 v109, v150, v152
	v_exp_f32_e32 v90, v90
	v_exp_f32_e32 v91, v91
	v_exp_f32_e32 v92, v92
	v_exp_f32_e32 v93, v93
	v_add_f32_e32 v106, v103, v106
	v_add_f32_e32 v107, v105, v107
	v_add_f32_e32 v108, v101, v108
	v_add_f32_e32 v109, v104, v109
	v_exp_f32_e32 v94, v94
	v_exp_f32_e32 v95, v95
	v_exp_f32_e32 v96, v96
	v_exp_f32_e32 v97, v97
	v_add_f32_e32 v106, v99, v106
	v_add_f32_e32 v107, v102, v107
	v_add_f32_e32 v108, v98, v108
	v_add_f32_e32 v109, v100, v109
	v_add_f32_e32 v106, v82, v106
	v_add_f32_e32 v107, v107, v83
	v_add_f32_e32 v108, v108, v84
	v_add_f32_e32 v109, v109, v85
	v_add_f32_e32 v106, v86, v106
	v_add_f32_e32 v107, v87, v107
	v_add_f32_e32 v108, v88, v108
	v_add_f32_e32 v109, v89, v109
	v_add_f32_e32 v106, v90, v106
	v_add_f32_e32 v107, v91, v107
	v_add_f32_e32 v108, v92, v108
	v_add_f32_e32 v109, v93, v109
	v_add_f32_e32 v106, v94, v106
	v_add_f32_e32 v107, v95, v107
	v_add_f32_e32 v108, v96, v108
	v_add_f32_e32 v109, v97, v109
	v_add_f32_e32 v106, v106, v107
	v_add_f32_e32 v107, v108, v109
	v_add_f32_e32 v233, v106, v107
	s_waitcnt lgkmcnt(0)
	s_barrier
	v_mov_b32_e32 v234, v233
	v_cvt_pk_bf16_f32 v146, v146, v153
	v_cvt_pk_bf16_f32 v147, v147, v152
	v_cvt_pk_bf16_f32 v148, v148, v151
	v_cvt_pk_bf16_f32 v149, v149, v150
	v_cvt_pk_bf16_f32 v150, v103, v105
	v_cvt_pk_bf16_f32 v151, v101, v104
	v_cvt_pk_bf16_f32 v152, v99, v102
	v_cvt_pk_bf16_f32 v153, v98, v100
	v_cvt_pk_bf16_f32 v158, v82, v83
	v_cvt_pk_bf16_f32 v159, v84, v85
	v_cvt_pk_bf16_f32 v160, v86, v87
	v_cvt_pk_bf16_f32 v161, v88, v89
	v_cvt_pk_bf16_f32 v154, v90, v91
	v_cvt_pk_bf16_f32 v155, v92, v93
	v_cvt_pk_bf16_f32 v156, v94, v95
	v_cvt_pk_bf16_f32 v157, v96, v97
	s_nop 1
	v_permlane32_swap_b32_e32 v233, v234
	v_cmp_neq_f32_e64 s[6:7], v232, -v231
	s_cmp_eq_u64 s[6:7], 0
	s_cselect_b64 s[6:7], -1, 0
	v_cndmask_b32_e64 v97, -v231, v81, s[6:7]
	v_cndmask_b32_e64 v96, -v231, v80, s[6:7]
	v_cndmask_b32_e64 v95, -v231, v79, s[6:7]
	v_cndmask_b32_e64 v94, -v231, v78, s[6:7]
	v_cndmask_b32_e64 v93, -v231, v77, s[6:7]
	v_cndmask_b32_e64 v92, -v231, v76, s[6:7]
	v_cndmask_b32_e64 v91, -v231, v75, s[6:7]
	v_cndmask_b32_e64 v90, -v231, v74, s[6:7]
	v_cndmask_b32_e64 v89, -v231, v73, s[6:7]
	v_cndmask_b32_e64 v88, -v231, v72, s[6:7]
	v_cndmask_b32_e64 v87, -v231, v71, s[6:7]
	v_cndmask_b32_e64 v86, -v231, v70, s[6:7]
	v_cndmask_b32_e64 v85, -v231, v69, s[6:7]
	v_cndmask_b32_e64 v84, -v231, v68, s[6:7]
	v_cndmask_b32_e64 v83, -v231, v67, s[6:7]
	v_cndmask_b32_e64 v82, -v231, v66, s[6:7]
	ds_read_b128 v[66:69], v200 offset:0
	ds_read_b128 v[162:165], v200 offset:0x2000
	ds_read_b128 v[166:169], v210 offset:0
	ds_read_b128 v[170:173], v210 offset:0x2000
	ds_read_b128 v[174:177], v211 offset:0
	ds_read_b128 v[192:195], v211 offset:0x2000
	s_waitcnt lgkmcnt(4)
	s_nop 1
	v_mfma_f32_32x32x16_bf16 v[98:113], v[66:69], v[142:145], v[82:97]
	v_mfma_f32_32x32x16_bf16 v[66:81], v[162:165], v[142:145], v[82:97]
	ds_read_b128 v[162:165], v212 offset:0
	ds_read_b128 v[236:239], v212 offset:0x2000
	s_waitcnt lgkmcnt(4)
	v_mfma_f32_32x32x16_bf16 v[98:113], v[166:169], v[138:141], v[98:113]
	ds_read_b128 v[166:169], v213 offset:0
	v_mfma_f32_32x32x16_bf16 v[66:81], v[170:173], v[138:141], v[66:81]
	ds_read_b128 v[170:173], v213 offset:0x2000
	s_waitcnt lgkmcnt(4)
	v_mfma_f32_32x32x16_bf16 v[98:113], v[174:177], v[134:137], v[98:113]
	ds_read_b128 v[174:177], v214 offset:0
	v_mfma_f32_32x32x16_bf16 v[66:81], v[192:195], v[134:137], v[66:81]
	ds_read_b128 v[192:195], v214 offset:0x2000
	s_waitcnt lgkmcnt(4)
	v_mfma_f32_32x32x16_bf16 v[98:113], v[162:165], v[130:133], v[98:113]
	ds_read_b128 v[162:165], v215 offset:0
	v_mfma_f32_32x32x16_bf16 v[66:81], v[236:239], v[130:133], v[66:81]
	ds_read_b128 v[236:239], v215 offset:0x2000
	s_waitcnt lgkmcnt(4)
	v_mfma_f32_32x32x16_bf16 v[98:113], v[166:169], v[126:129], v[98:113]
	ds_read_b128 v[166:169], v216 offset:0
	v_mfma_f32_32x32x16_bf16 v[66:81], v[170:173], v[126:129], v[66:81]
	ds_read_b128 v[170:173], v216 offset:0x2000
	s_waitcnt lgkmcnt(4)
	v_mfma_f32_32x32x16_bf16 v[98:113], v[174:177], v[122:125], v[98:113]
	s_waitcnt lgkmcnt(2)
	v_mfma_f32_32x32x16_bf16 v[66:81], v[192:195], v[122:125], v[66:81]
	v_mfma_f32_32x32x16_bf16 v[98:113], v[162:165], v[118:121], v[98:113]
	s_waitcnt lgkmcnt(0)
	v_mfma_f32_32x32x16_bf16 v[66:81], v[236:239], v[118:121], v[66:81]
	v_mfma_f32_32x32x16_bf16 v[98:113], v[166:169], v[114:117], v[98:113]
	v_mfma_f32_32x32x16_bf16 v[66:81], v[170:173], v[114:117], v[66:81]
	s_nop 10
	v_max_f32_e32 v162, v98, v102
	v_max_f32_e32 v163, v99, v103
	v_max_f32_e32 v164, v101, v105
	v_max3_f32 v165, v100, v104, v108
	v_max3_f32 v164, v164, v109, v113
	v_max3_f32 v162, v162, v106, v110
	v_max3_f32 v163, v163, v107, v111
	v_max3_f32 v165, v165, v112, v68
	v_max3_f32 v164, v164, v69, v73
	v_max3_f32 v162, v162, v66, v70
	v_max3_f32 v163, v163, v67, v71
	v_max3_f32 v165, v165, v72, v76
	v_max3_f32 v164, v164, v77, v81
	v_max3_f32 v162, v162, v74, v78
	v_max3_f32 v163, v163, v75, v79
	v_max3_f32 v164, v165, v80, v164
	v_max3_f32 v162, v162, v163, v164
	v_mov_b32_e32 v163, v162
	s_nop 1
	v_permlane32_swap_b32_e32 v162, v163
	v_max_f32_e32 v162, v162, v163
	v_cmp_ge_f32_e32 vcc, s48, v162
	s_cmp_eq_u64 vcc, exec
	v_mov_b32_e32 v226, 1.0
	s_cbranch_scc0 .LBB0_436
	v_mov_b32_e32 v227, v231

; __device__ __forceinline__ void qkt8_roll(f32x16& p0, f32x16& p1, const f32x16& negm, int kb, const bf16x8* qr) {
;   const int a0 = kb ^ (0 << 5); const bf16x8 x0 = lds_rd128<0>(a0), y0 = lds_rd128<8192>(a0);
;   const int a1 = kb ^ (1 << 5); const bf16x8 x1 = lds_rd128<0>(a1), y1 = lds_rd128<8192>(a1);
;   const int a2 = kb ^ (2 << 5); const bf16x8 x2 = lds_rd128<0>(a2), y2 = lds_rd128<8192>(a2);
;   asm volatile("s_waitcnt lgkmcnt(4)" ::: "memory"); SBAR_M();
;   p0 = __builtin_amdgcn_mfma_f32_32x32x16_bf16(x0, qr[0], negm, 0, 0, 0); p1 = __builtin_amdgcn_mfma_f32_32x32x16_bf16(y0, qr[0], negm, 0, 0, 0);
;   const int a3 = kb ^ (3 << 5); const bf16x8 x3 = lds_rd128<0>(a3), y3 = lds_rd128<8192>(a3);
;   asm volatile("s_waitcnt lgkmcnt(4)" ::: "memory"); SBAR_M();
;   p0 = __builtin_amdgcn_mfma_f32_32x32x16_bf16(x1, qr[1], p0, 0, 0, 0); p1 = __builtin_amdgcn_mfma_f32_32x32x16_bf16(y1, qr[1], p1, 0, 0, 0);
;   const int a4 = kb ^ (4 << 5); const bf16x8 x4 = lds_rd128<0>(a4), y4 = lds_rd128<8192>(a4);
;   asm volatile("s_waitcnt lgkmcnt(4)" ::: "memory"); SBAR_M();
;   p0 = __builtin_amdgcn_mfma_f32_32x32x16_bf16(x2, qr[2], p0, 0, 0, 0); p1 = __builtin_amdgcn_mfma_f32_32x32x16_bf16(y2, qr[2], p1, 0, 0, 0);
;   const int a5 = kb ^ (5 << 5); const bf16x8 x5 = lds_rd128<0>(a5), y5 = lds_rd128<8192>(a5);
;   asm volatile("s_waitcnt lgkmcnt(4)" ::: "memory"); SBAR_M();
;   p0 = __builtin_amdgcn_mfma_f32_32x32x16_bf16(x3, qr[3], p0, 0, 0, 0); p1 = __builtin_amdgcn_mfma_f32_32x32x16_bf16(y3, qr[3], p1, 0, 0, 0);
;   const int a6 = kb ^ (6 << 5); const bf16x8 x6 = lds_rd128<0>(a6), y6 = lds_rd128<8192>(a6);
;   asm volatile("s_waitcnt lgkmcnt(4)" ::: "memory"); SBAR_M();
;   p0 = __builtin_amdgcn_mfma_f32_32x32x16_bf16(x4, qr[4], p0, 0, 0, 0); p1 = __builtin_amdgcn_mfma_f32_32x32x16_bf16(y4, qr[4], p1, 0, 0, 0);
;   const int a7 = kb ^ (7 << 5); const bf16x8 x7 = lds_rd128<0>(a7), y7 = lds_rd128<8192>(a7);
;   asm volatile("s_waitcnt lgkmcnt(4)" ::: "memory"); SBAR_M();
;   p0 = __builtin_amdgcn_mfma_f32_32x32x16_bf16(x5, qr[5], p0, 0, 0, 0); p1 = __builtin_amdgcn_mfma_f32_32x32x16_bf16(y5, qr[5], p1, 0, 0, 0);
;   asm volatile("s_waitcnt lgkmcnt(2)" ::: "memory"); SBAR_M();
;   p0 = __builtin_amdgcn_mfma_f32_32x32x16_bf16(x6, qr[6], p0, 0, 0, 0); p1 = __builtin_amdgcn_mfma_f32_32x32x16_bf16(y6, qr[6], p1, 0, 0, 0);
.LBB0_447:
	v_cmp_neq_f32_e64 s[6:7], v231, -v228
	s_cmp_eq_u64 s[6:7], 0
	s_cselect_b64 s[6:7], -1, 0
	v_cndmask_b32_e64 v97, -v228, v97, s[6:7]
	v_cndmask_b32_e64 v96, -v228, v96, s[6:7]
	v_cndmask_b32_e64 v95, -v228, v95, s[6:7]
	v_cndmask_b32_e64 v94, -v228, v94, s[6:7]
	v_cndmask_b32_e64 v93, -v228, v93, s[6:7]
	v_cndmask_b32_e64 v92, -v228, v92, s[6:7]
	v_cndmask_b32_e64 v91, -v228, v91, s[6:7]
	v_cndmask_b32_e64 v90, -v228, v90, s[6:7]
	v_cndmask_b32_e64 v89, -v228, v89, s[6:7]
	v_cndmask_b32_e64 v88, -v228, v88, s[6:7]
	v_cndmask_b32_e64 v87, -v228, v87, s[6:7]
	v_cndmask_b32_e64 v86, -v228, v86, s[6:7]
	v_cndmask_b32_e64 v85, -v228, v85, s[6:7]
	v_cndmask_b32_e64 v84, -v228, v84, s[6:7]
	v_cndmask_b32_e64 v83, -v228, v83, s[6:7]
	v_cndmask_b32_e64 v82, -v228, v82, s[6:7]
	ds_read_b128 v[98:101], v224 offset:0
	ds_read_b128 v[232:235], v224 offset:0x2000
	ds_read_b128 v[236:239], v223 offset:0
	ds_read_b128 v[240:243], v223 offset:0x2000
	ds_read_b128 v[244:247], v222 offset:0
	ds_read_b128 v[248:251], v222 offset:0x2000
	s_waitcnt lgkmcnt(4)
	s_nop 1
	v_mfma_f32_32x32x16_bf16 v[114:129], v[98:101], v[158:161], v[82:97]
	v_mfma_f32_32x32x16_bf16 v[98:113], v[232:235], v[158:161], v[82:97]
	ds_read_b128 v[232:235], v221 offset:0
	ds_read_b128 v[190:193], v221 offset:0x2000
	s_waitcnt lgkmcnt(4)
	v_mfma_f32_32x32x16_bf16 v[114:129], v[236:239], v[154:157], v[114:129]
	ds_read_b128 v[236:239], v220 offset:0
	v_mfma_f32_32x32x16_bf16 v[98:113], v[240:243], v[154:157], v[98:113]
	ds_read_b128 v[240:243], v220 offset:0x2000
	s_waitcnt lgkmcnt(4)
	v_mfma_f32_32x32x16_bf16 v[114:129], v[244:247], v[150:153], v[114:129]
	ds_read_b128 v[244:247], v219 offset:0
	v_mfma_f32_32x32x16_bf16 v[98:113], v[248:251], v[150:153], v[98:113]
	ds_read_b128 v[248:251], v219 offset:0x2000
	s_waitcnt lgkmcnt(4)
	v_mfma_f32_32x32x16_bf16 v[114:129], v[232:235], v[146:149], v[114:129]
	v_mfma_f32_32x32x16_bf16 v[98:113], v[190:193], v[146:149], v[98:113]
	ds_read_b128 v[190:193], v218 offset:0
	ds_read_b128 v[232:235], v218 offset:0x2000
	s_waitcnt lgkmcnt(4)
	v_mfma_f32_32x32x16_bf16 v[114:129], v[236:239], v[142:145], v[114:129]
	ds_read_b128 v[236:239], v217 offset:0
	v_mfma_f32_32x32x16_bf16 v[98:113], v[240:243], v[142:145], v[98:113]
	ds_read_b128 v[240:243], v217 offset:0x2000
	s_waitcnt lgkmcnt(4)
	v_mfma_f32_32x32x16_bf16 v[114:129], v[244:247], v[138:141], v[114:129]
	s_waitcnt lgkmcnt(2)
	v_mfma_f32_32x32x16_bf16 v[98:113], v[248:251], v[138:141], v[98:113]
	v_mfma_f32_32x32x16_bf16 v[114:129], v[190:193], v[134:137], v[114:129]
	s_waitcnt lgkmcnt(0)
	v_mfma_f32_32x32x16_bf16 v[98:113], v[232:235], v[134:137], v[98:113]
	v_exp_f32_e32 v66, v66
	v_exp_f32_e32 v67, v67
	v_exp_f32_e32 v68, v68
	v_exp_f32_e32 v69, v69
	v_exp_f32_e32 v70, v70
	v_exp_f32_e32 v71, v71
	v_exp_f32_e32 v72, v72
	v_exp_f32_e32 v73, v73
	v_add_f32_e32 v162, v164, v176
	v_add_f32_e32 v189, v175, v188
	v_add_f32_e32 v190, v165, v163
	v_add_f32_e32 v191, v174, v177
	v_exp_f32_e32 v74, v74
	v_exp_f32_e32 v75, v75
	v_exp_f32_e32 v76, v76
	v_exp_f32_e32 v77, v77
	v_add_f32_e32 v162, v166, v162
	v_add_f32_e32 v189, v173, v189
	v_add_f32_e32 v190, v167, v190
	v_add_f32_e32 v191, v172, v191
	v_exp_f32_e32 v78, v78
	v_exp_f32_e32 v79, v79
	v_exp_f32_e32 v80, v80
	v_exp_f32_e32 v81, v81
	v_add_f32_e32 v162, v168, v162
	v_add_f32_e32 v189, v171, v189
	v_add_f32_e32 v190, v169, v190
	v_add_f32_e32 v191, v170, v191
	v_mfma_f32_32x32x16_bf16 v[114:129], v[236:239], v[130:133], v[114:129]
	v_add_f32_e32 v162, v66, v162
	v_add_f32_e32 v189, v67, v189
	v_add_f32_e32 v190, v68, v190
	v_add_f32_e32 v191, v69, v191
	v_add_f32_e32 v162, v70, v162
	v_add_f32_e32 v189, v71, v189
	v_add_f32_e32 v190, v72, v190
	v_mfma_f32_32x32x16_bf16 v[98:113], v[240:243], v[130:133], v[98:113]
	v_add_f32_e32 v191, v73, v191
	v_add_f32_e32 v162, v74, v162
	v_add_f32_e32 v189, v75, v189
	v_add_f32_e32 v190, v76, v190
	v_add_f32_e32 v191, v77, v191
	v_add_f32_e32 v162, v78, v162
	v_add_f32_e32 v189, v79, v189
	v_add_f32_e32 v190, v80, v190
	v_add_f32_e32 v191, v81, v191
	v_add_f32_e32 v162, v162, v189
	v_add_f32_e32 v189, v190, v191
	v_add_f32_e32 v226, v162, v189
	v_mov_b32_e32 v227, v226
	v_cvt_pk_bf16_f32 v162, v176, v188
	v_cvt_pk_bf16_f32 v163, v163, v177
	v_cvt_pk_bf16_f32 v164, v164, v175
	s_nop 1
	v_permlane32_swap_b32_e32 v226, v227
	v_cvt_pk_bf16_f32 v165, v165, v174
	v_cvt_pk_bf16_f32 v166, v166, v173
	v_cvt_pk_bf16_f32 v167, v167, v172
	v_cvt_pk_bf16_f32 v168, v168, v171
	v_cvt_pk_bf16_f32 v169, v169, v170
	v_cvt_pk_bf16_f32 v170, v66, v67
	v_cvt_pk_bf16_f32 v171, v68, v69
	v_cvt_pk_bf16_f32 v172, v70, v71
	v_cvt_pk_bf16_f32 v173, v72, v73
	v_cvt_pk_bf16_f32 v174, v74, v75
	v_cvt_pk_bf16_f32 v175, v76, v77
	v_cvt_pk_bf16_f32 v176, v78, v79
	v_cvt_pk_bf16_f32 v177, v80, v81
	v_lshl_add_u64 v[188:189], v[186:187], 0, v[0:1]
	v_add_co_u32_e32 v66, vcc, s78, v188
	v_lshl_add_u64 v[190:191], v[184:185], 0, v[0:1]
	s_nop 0
	v_addc_co_u32_e32 v67, vcc, 0, v189, vcc
	v_add_co_u32_e32 v70, vcc, s79, v188
	s_nop 1
	v_addc_co_u32_e32 v71, vcc, 0, v189, vcc
	v_add_co_u32_e32 v74, vcc, s70, v190
	global_load_dwordx4 v[66:69], v[66:67], off offset:2176
	s_nop 0
	global_load_dwordx4 v[70:73], v[70:71], off offset:2176
	v_addc_co_u32_e32 v75, vcc, 0, v191, vcc
	v_add_co_u32_e32 v78, vcc, s71, v190
	s_nop 1
	v_addc_co_u32_e32 v79, vcc, 0, v191, vcc
	global_load_dwordx4 v[74:77], v[74:75], off
	s_nop 0
	global_load_dwordx4 v[78:81], v[78:79], off
	ds_read_b64_tr_b16 v[232:233], v199 offset:0
	ds_read_b64_tr_b16 v[234:235], v199 offset:0x800
	ds_read_b64_tr_b16 v[236:237], v199 offset:0x1000
	ds_read_b64_tr_b16 v[238:239], v199 offset:0x1800
	ds_read_b64_tr_b16 v[240:241], v199 offset:0x2000
	ds_read_b64_tr_b16 v[242:243], v199 offset:0x2800
	ds_read_b64_tr_b16 v[244:245], v199 offset:0x3000
	ds_read_b64_tr_b16 v[246:247], v199 offset:0x3800
	ds_read_b64_tr_b16 v[248:249], v199 offset:0x200
	ds_read_b64_tr_b16 v[250:251], v199 offset:0xa00
	s_waitcnt lgkmcnt(8)
; __device__ __forceinline__ void pv_d0(f32x16* o, int vb, bf16x8 pa0, bf16x8 pa1, bf16x8 pa2, bf16x8 pa3) {
;     ...
;   const s16x4 l0 = tr_read<v_rd_off(0, 0, 0)>(vb), h0 = tr_read<v_rd_off(0, 0, 1)>(vb);
;   const s16x4 l1 = tr_read<v_rd_off(0, 1, 0)>(vb), h1 = tr_read<v_rd_off(0, 1, 1)>(vb);
;   const s16x4 l2 = tr_read<v_rd_off(0, 2, 0)>(vb), h2 = tr_read<v_rd_off(0, 2, 1)>(vb);
;   const s16x4 l3 = tr_read<v_rd_off(0, 3, 0)>(vb), h3 = tr_read<v_rd_off(0, 3, 1)>(vb);
;   const s16x4 l4 = tr_read<v_rd_off(1, 0, 0)>(vb), h4 = tr_read<v_rd_off(1, 0, 1)>(vb);
;   asm volatile("s_waitcnt lgkmcnt(8)" ::: "memory"); SBAR();
;   o[0] = __builtin_amdgcn_mfma_f32_32x32x16_bf16(pa0, PK(l0, h0), o[0], 0, 0, 0);
;   const s16x4 l5 = tr_read<v_rd_off(1, 1, 0)>(vb), h5 = tr_read<v_rd_off(1, 1, 1)>(vb);
;   asm volatile("s_waitcnt lgkmcnt(8)" ::: "memory"); SBAR();
;   o[0] = __builtin_amdgcn_mfma_f32_32x32x16_bf16(pa1, PK(l1, h1), o[0], 0, 0, 0);
;   const s16x4 l6 = tr_read<v_rd_off(1, 2, 0)>(vb), h6 = tr_read<v_rd_off(1, 2, 1)>(vb);
;   asm volatile("s_waitcnt lgkmcnt(8)" ::: "memory"); SBAR();
;   o[0] = __builtin_amdgcn_mfma_f32_32x32x16_bf16(pa2, PK(l2, h2), o[0], 0, 0, 0);
;   const s16x4 l7 = tr_read<v_rd_off(1, 3, 0)>(vb), h7 = tr_read<v_rd_off(1, 3, 1)>(vb);
;   asm volatile("s_waitcnt lgkmcnt(8)" ::: "memory"); SBAR();
;   o[0] = __builtin_amdgcn_mfma_f32_32x32x16_bf16(pa3, PK(l3, h3), o[0], 0, 0, 0);
;   const s16x4 l8 = tr_read<v_rd_off(2, 0, 0)>(vb), h8 = tr_read<v_rd_off(2, 0, 1)>(vb);
;   asm volatile("s_waitcnt lgkmcnt(8)" ::: "memory"); SBAR();
;   o[1] = __builtin_amdgcn_mfma_f32_32x32x16_bf16(pa0, PK(l4, h4), o[1], 0, 0, 0);
;   const s16x4 l9 = tr_read<v_rd_off(2, 1, 0)>(vb), h9 = tr_read<v_rd_off(2, 1, 1)>(vb);
;   asm volatile("s_waitcnt lgkmcnt(8)" ::: "memory"); SBAR();
;   o[1] = __builtin_amdgcn_mfma_f32_32x32x16_bf16(pa1, PK(l5, h5), o[1], 0, 0, 0);
;   const s16x4 l10 = tr_read<v_rd_off(2, 2, 0)>(vb), h10 = tr_read<v_rd_off(2, 2, 1)>(vb);
;   asm volatile("s_waitcnt lgkmcnt(8)" ::: "memory"); SBAR();
;   o[1] = __builtin_amdgcn_mfma_f32_32x32x16_bf16(pa2, PK(l6, h6), o[1], 0, 0, 0);
;   const s16x4 l11 = tr_read<v_rd_off(2, 3, 0)>(vb), h11 = tr_read<v_rd_off(2, 3, 1)>(vb);
;   asm volatile("s_waitcnt lgkmcnt(8)" ::: "memory"); SBAR();
;   o[1] = __builtin_amdgcn_mfma_f32_32x32x16_bf16(pa3, PK(l7, h7), o[1], 0, 0, 0);
	s_nop 0
	v_mfma_f32_32x32x16_bf16 v[2:17], v[162:165], v[232:235], v[2:17]
	ds_read_b64_tr_b16 v[232:233], v199 offset:0x1200
	ds_read_b64_tr_b16 v[234:235], v199 offset:0x1a00
	s_waitcnt lgkmcnt(8)
	v_mfma_f32_32x32x16_bf16 v[2:17], v[166:169], v[236:239], v[2:17]
	ds_read_b64_tr_b16 v[236:237], v199 offset:0x2200
	ds_read_b64_tr_b16 v[238:239], v199 offset:0x2a00
	s_waitcnt lgkmcnt(8)
	v_mfma_f32_32x32x16_bf16 v[2:17], v[170:173], v[240:243], v[2:17]
	ds_read_b64_tr_b16 v[240:241], v199 offset:0x3200
	ds_read_b64_tr_b16 v[242:243], v199 offset:0x3a00
	s_waitcnt lgkmcnt(8)
	v_mfma_f32_32x32x16_bf16 v[2:17], v[174:177], v[244:247], v[2:17]
	ds_read_b64_tr_b16 v[244:245], v199 offset:0x400
	ds_read_b64_tr_b16 v[246:247], v199 offset:0xc00
	s_waitcnt lgkmcnt(8)
	v_mfma_f32_32x32x16_bf16 v[50:65], v[162:165], v[248:251], v[50:65]
	ds_read_b64_tr_b16 v[248:249], v199 offset:0x1400
	ds_read_b64_tr_b16 v[250:251], v199 offset:0x1c00
	s_waitcnt lgkmcnt(8)
	v_mfma_f32_32x32x16_bf16 v[50:65], v[166:169], v[232:235], v[50:65]
	ds_read_b64_tr_b16 v[232:233], v199 offset:0x2400
	ds_read_b64_tr_b16 v[234:235], v199 offset:0x2c00
	s_waitcnt lgkmcnt(8)
	v_mfma_f32_32x32x16_bf16 v[50:65], v[170:173], v[236:239], v[50:65]
	ds_read_b64_tr_b16 v[236:237], v199 offset:0x3400
	ds_read_b64_tr_b16 v[238:239], v199 offset:0x3c00
	s_waitcnt lgkmcnt(8)
	v_mfma_f32_32x32x16_bf16 v[50:65], v[174:177], v[240:243], v[50:65]
	ds_read_b64_tr_b16 v[240:241], v199 offset:0x600
	ds_read_b64_tr_b16 v[242:243], v199 offset:0xe00
	s_waitcnt lgkmcnt(8)
	v_mfma_f32_32x32x16_bf16 v[34:49], v[162:165], v[244:247], v[34:49]
	ds_read_b64_tr_b16 v[244:245], v199 offset:0x1600
	ds_read_b64_tr_b16 v[246:247], v199 offset:0x1e00
	s_waitcnt lgkmcnt(8)
	v_mfma_f32_32x32x16_bf16 v[34:49], v[166:169], v[248:251], v[34:49]
	ds_read_b64_tr_b16 v[248:249], v199 offset:0x2600
	ds_read_b64_tr_b16 v[250:251], v199 offset:0x2e00
	s_waitcnt lgkmcnt(8)
	v_mfma_f32_32x32x16_bf16 v[34:49], v[170:173], v[232:235], v[34:49]
	ds_read_b64_tr_b16 v[232:233], v199 offset:0x3600
	ds_read_b64_tr_b16 v[234:235], v199 offset:0x3e00
	s_waitcnt lgkmcnt(8)
	v_mfma_f32_32x32x16_bf16 v[34:49], v[174:177], v[236:239], v[34:49]
	s_waitcnt lgkmcnt(6)
	v_mfma_f32_32x32x16_bf16 v[18:33], v[162:165], v[240:243], v[18:33]
	s_waitcnt lgkmcnt(4)
	v_mfma_f32_32x32x16_bf16 v[18:33], v[166:169], v[244:247], v[18:33]
	s_waitcnt lgkmcnt(2)
	v_mfma_f32_32x32x16_bf16 v[18:33], v[170:173], v[248:251], v[18:33]
	s_waitcnt lgkmcnt(0)
	v_max_f32_e32 v162, v114, v118
	v_max_f32_e32 v163, v115, v119
	v_max_f32_e32 v164, v117, v121
	v_max3_f32 v165, v116, v120, v124
	v_max3_f32 v164, v164, v125, v129
	v_max3_f32 v162, v162, v122, v126
	v_max3_f32 v163, v163, v123, v127
	v_max3_f32 v165, v165, v128, v100
	v_max3_f32 v164, v164, v101, v105
	v_max3_f32 v162, v162, v98, v102
	v_max3_f32 v163, v163, v99, v103
	v_max3_f32 v165, v165, v104, v108
	v_max3_f32 v164, v164, v109, v113
	v_mfma_f32_32x32x16_bf16 v[18:33], v[174:177], v[232:235], v[18:33]
	v_max3_f32 v162, v162, v106, v110
	v_max3_f32 v163, v163, v107, v111
	v_max3_f32 v164, v165, v112, v164
	v_max3_f32 v162, v162, v163, v164
	v_mov_b32_e32 v163, v162
	s_nop 1
	v_permlane32_swap_b32_e32 v162, v163
	v_max_f32_e32 v162, v162, v163
	v_cmp_ge_f32_e32 vcc, s48, v162
	s_cmp_eq_u64 vcc, exec
	s_cbranch_scc0 .LBB0_461
	v_mov_b32_e32 v230, v228
	v_mov_b32_e32 v229, 1.0

; __device__ __forceinline__ void qkt8_roll(f32x16& p0, f32x16& p1, const f32x16& negm, int kb, const bf16x8* qr) {
;   const int a0 = kb ^ (0 << 5); const bf16x8 x0 = lds_rd128<0>(a0), y0 = lds_rd128<8192>(a0);
;   const int a1 = kb ^ (1 << 5); const bf16x8 x1 = lds_rd128<0>(a1), y1 = lds_rd128<8192>(a1);
;   const int a2 = kb ^ (2 << 5); const bf16x8 x2 = lds_rd128<0>(a2), y2 = lds_rd128<8192>(a2);
;   asm volatile("s_waitcnt lgkmcnt(4)" ::: "memory"); SBAR_M();
;   p0 = __builtin_amdgcn_mfma_f32_32x32x16_bf16(x0, qr[0], negm, 0, 0, 0); p1 = __builtin_amdgcn_mfma_f32_32x32x16_bf16(y0, qr[0], negm, 0, 0, 0);
;   const int a3 = kb ^ (3 << 5); const bf16x8 x3 = lds_rd128<0>(a3), y3 = lds_rd128<8192>(a3);
;   asm volatile("s_waitcnt lgkmcnt(4)" ::: "memory"); SBAR_M();
;   p0 = __builtin_amdgcn_mfma_f32_32x32x16_bf16(x1, qr[1], p0, 0, 0, 0); p1 = __builtin_amdgcn_mfma_f32_32x32x16_bf16(y1, qr[1], p1, 0, 0, 0);
;   const int a4 = kb ^ (4 << 5); const bf16x8 x4 = lds_rd128<0>(a4), y4 = lds_rd128<8192>(a4);
;   asm volatile("s_waitcnt lgkmcnt(4)" ::: "memory"); SBAR_M();
;   p0 = __builtin_amdgcn_mfma_f32_32x32x16_bf16(x2, qr[2], p0, 0, 0, 0); p1 = __builtin_amdgcn_mfma_f32_32x32x16_bf16(y2, qr[2], p1, 0, 0, 0);
;   const int a5 = kb ^ (5 << 5); const bf16x8 x5 = lds_rd128<0>(a5), y5 = lds_rd128<8192>(a5);
;   asm volatile("s_waitcnt lgkmcnt(4)" ::: "memory"); SBAR_M();
;   p0 = __builtin_amdgcn_mfma_f32_32x32x16_bf16(x3, qr[3], p0, 0, 0, 0); p1 = __builtin_amdgcn_mfma_f32_32x32x16_bf16(y3, qr[3], p1, 0, 0, 0);
;   const int a6 = kb ^ (6 << 5); const bf16x8 x6 = lds_rd128<0>(a6), y6 = lds_rd128<8192>(a6);
;   asm volatile("s_waitcnt lgkmcnt(4)" ::: "memory"); SBAR_M();
;   p0 = __builtin_amdgcn_mfma_f32_32x32x16_bf16(x4, qr[4], p0, 0, 0, 0); p1 = __builtin_amdgcn_mfma_f32_32x32x16_bf16(y4, qr[4], p1, 0, 0, 0);
;   const int a7 = kb ^ (7 << 5); const bf16x8 x7 = lds_rd128<0>(a7), y7 = lds_rd128<8192>(a7);
;   asm volatile("s_waitcnt lgkmcnt(4)" ::: "memory"); SBAR_M();
;   p0 = __builtin_amdgcn_mfma_f32_32x32x16_bf16(x5, qr[5], p0, 0, 0, 0); p1 = __builtin_amdgcn_mfma_f32_32x32x16_bf16(y5, qr[5], p1, 0, 0, 0);
;   asm volatile("s_waitcnt lgkmcnt(2)" ::: "memory"); SBAR_M();
;   p0 = __builtin_amdgcn_mfma_f32_32x32x16_bf16(x6, qr[6], p0, 0, 0, 0); p1 = __builtin_amdgcn_mfma_f32_32x32x16_bf16(y6, qr[6], p1, 0, 0, 0);
.LBB0_453:
	v_xor_b32_e32 v66, 0x80000000, v228
	v_cndmask_b32_e64 v231, v66, v231, s[6:7]
	v_exp_f32_e32 v162, v114
	v_exp_f32_e32 v163, v116
	v_cmp_neq_f32_e64 s[6:7], v231, -v230
	s_cmp_eq_u64 s[6:7], 0
	s_cselect_b64 s[6:7], -1, 0
	v_cndmask_b32_e64 v97, -v230, v97, s[6:7]
	v_cndmask_b32_e64 v96, -v230, v96, s[6:7]
	v_cndmask_b32_e64 v95, -v230, v95, s[6:7]
	v_cndmask_b32_e64 v94, -v230, v94, s[6:7]
	v_cndmask_b32_e64 v93, -v230, v93, s[6:7]
	v_cndmask_b32_e64 v92, -v230, v92, s[6:7]
	v_cndmask_b32_e64 v91, -v230, v91, s[6:7]
	v_cndmask_b32_e64 v90, -v230, v90, s[6:7]
	v_cndmask_b32_e64 v89, -v230, v89, s[6:7]
	v_cndmask_b32_e64 v88, -v230, v88, s[6:7]
	v_cndmask_b32_e64 v87, -v230, v87, s[6:7]
	v_cndmask_b32_e64 v86, -v230, v86, s[6:7]
	v_cndmask_b32_e64 v85, -v230, v85, s[6:7]
	v_cndmask_b32_e64 v84, -v230, v84, s[6:7]
	v_cndmask_b32_e64 v83, -v230, v83, s[6:7]
	v_cndmask_b32_e64 v82, -v230, v82, s[6:7]
	v_exp_f32_e32 v177, v115
	v_exp_f32_e32 v176, v117
	v_exp_f32_e32 v164, v118
	v_exp_f32_e32 v175, v119
	v_exp_f32_e32 v165, v120
	v_exp_f32_e32 v174, v121
	v_exp_f32_e32 v166, v122
	v_exp_f32_e32 v173, v123
	v_exp_f32_e32 v167, v124
	v_exp_f32_e32 v172, v125
	v_exp_f32_e32 v168, v126
	v_exp_f32_e32 v171, v127
	v_exp_f32_e32 v169, v128
	v_exp_f32_e32 v170, v129
	s_waitcnt lgkmcnt(0)
	s_barrier
	ds_read_b128 v[66:69], v200 offset:0
	ds_read_b128 v[232:235], v200 offset:0x2000
	ds_read_b128 v[236:239], v210 offset:0
	ds_read_b128 v[240:243], v210 offset:0x2000
	ds_read_b128 v[244:247], v211 offset:0
	ds_read_b128 v[248:251], v211 offset:0x2000
	s_waitcnt lgkmcnt(4)
	s_nop 0
	v_mfma_f32_32x32x16_bf16 v[114:129], v[66:69], v[158:161], v[82:97]
	v_mfma_f32_32x32x16_bf16 v[66:81], v[232:235], v[158:161], v[82:97]
	ds_read_b128 v[232:235], v212 offset:0
	ds_read_b128 v[192:195], v212 offset:0x2000
	s_waitcnt lgkmcnt(4)
	v_mfma_f32_32x32x16_bf16 v[114:129], v[236:239], v[154:157], v[114:129]
	ds_read_b128 v[236:239], v213 offset:0
	v_mfma_f32_32x32x16_bf16 v[66:81], v[240:243], v[154:157], v[66:81]
	ds_read_b128 v[240:243], v213 offset:0x2000
	s_waitcnt lgkmcnt(4)
	v_mfma_f32_32x32x16_bf16 v[114:129], v[244:247], v[150:153], v[114:129]
	ds_read_b128 v[244:247], v214 offset:0
	v_mfma_f32_32x32x16_bf16 v[66:81], v[248:251], v[150:153], v[66:81]
	ds_read_b128 v[248:251], v214 offset:0x2000
	s_waitcnt lgkmcnt(4)
	v_mfma_f32_32x32x16_bf16 v[114:129], v[232:235], v[146:149], v[114:129]
	v_mfma_f32_32x32x16_bf16 v[66:81], v[192:195], v[146:149], v[66:81]
	ds_read_b128 v[192:195], v215 offset:0
	ds_read_b128 v[232:235], v215 offset:0x2000
	s_waitcnt lgkmcnt(4)
	v_mfma_f32_32x32x16_bf16 v[114:129], v[236:239], v[142:145], v[114:129]
	ds_read_b128 v[236:239], v216 offset:0
	v_mfma_f32_32x32x16_bf16 v[66:81], v[240:243], v[142:145], v[66:81]
	ds_read_b128 v[240:243], v216 offset:0x2000
	s_waitcnt lgkmcnt(4)
	v_mfma_f32_32x32x16_bf16 v[114:129], v[244:247], v[138:141], v[114:129]
	s_waitcnt lgkmcnt(2)
	v_mfma_f32_32x32x16_bf16 v[66:81], v[248:251], v[138:141], v[66:81]
	v_mfma_f32_32x32x16_bf16 v[114:129], v[192:195], v[134:137], v[114:129]
	s_waitcnt lgkmcnt(0)
	v_mfma_f32_32x32x16_bf16 v[66:81], v[232:235], v[134:137], v[66:81]
	v_exp_f32_e32 v98, v98
	v_exp_f32_e32 v99, v99
	v_exp_f32_e32 v100, v100
	v_exp_f32_e32 v101, v101
	v_exp_f32_e32 v102, v102
	v_exp_f32_e32 v103, v103
	v_exp_f32_e32 v104, v104
	v_exp_f32_e32 v105, v105
	v_add_f32_e32 v192, v164, v162
	v_add_f32_e32 v193, v175, v177
	v_add_f32_e32 v194, v165, v163
	v_add_f32_e32 v195, v174, v176
	v_exp_f32_e32 v106, v106
	v_exp_f32_e32 v107, v107
	v_exp_f32_e32 v108, v108
	v_exp_f32_e32 v109, v109
	v_add_f32_e32 v192, v166, v192
	v_add_f32_e32 v193, v173, v193
	v_add_f32_e32 v194, v167, v194
	v_add_f32_e32 v195, v172, v195
	v_exp_f32_e32 v110, v110
	v_exp_f32_e32 v111, v111
	v_exp_f32_e32 v112, v112
	v_exp_f32_e32 v113, v113
	v_add_f32_e32 v192, v168, v192
	v_add_f32_e32 v193, v171, v193
	v_add_f32_e32 v194, v169, v194
	v_add_f32_e32 v195, v170, v195
	v_mfma_f32_32x32x16_bf16 v[114:129], v[236:239], v[130:133], v[114:129]
	v_add_f32_e32 v192, v98, v192
	v_add_f32_e32 v193, v193, v99
	v_add_f32_e32 v194, v194, v100
	v_add_f32_e32 v195, v195, v101
	v_add_f32_e32 v192, v102, v192
	v_add_f32_e32 v193, v103, v193
	v_add_f32_e32 v194, v104, v194
	v_mfma_f32_32x32x16_bf16 v[66:81], v[240:243], v[130:133], v[66:81]
	v_add_f32_e32 v195, v105, v195
	v_add_f32_e32 v192, v106, v192
	v_add_f32_e32 v193, v107, v193
	v_add_f32_e32 v194, v108, v194
	v_add_f32_e32 v195, v109, v195
	v_add_f32_e32 v192, v110, v192
	v_add_f32_e32 v193, v111, v193
	v_add_f32_e32 v194, v112, v194
	v_add_f32_e32 v195, v113, v195
	v_add_f32_e32 v192, v192, v193
	v_add_f32_e32 v193, v194, v195
	v_add_f32_e32 v232, v192, v193
	v_mov_b32_e32 v233, v232
	v_cvt_pk_bf16_f32 v162, v162, v177
	v_cvt_pk_bf16_f32 v163, v163, v176
	v_cvt_pk_bf16_f32 v164, v164, v175
	v_cvt_pk_bf16_f32 v165, v165, v174
	s_nop 1
	v_permlane32_swap_b32_e32 v232, v233
	v_cvt_pk_bf16_f32 v166, v166, v173
	v_cvt_pk_bf16_f32 v167, v167, v172
	v_cvt_pk_bf16_f32 v168, v168, v171
	v_cvt_pk_bf16_f32 v169, v169, v170
	v_cvt_pk_bf16_f32 v170, v98, v99
	v_cvt_pk_bf16_f32 v171, v100, v101
	v_cvt_pk_bf16_f32 v172, v102, v103
	v_cvt_pk_bf16_f32 v173, v104, v105
	v_cvt_pk_bf16_f32 v174, v106, v107
	v_cvt_pk_bf16_f32 v175, v108, v109
	v_cvt_pk_bf16_f32 v176, v110, v111
	v_cvt_pk_bf16_f32 v177, v112, v113
	s_nop 0
	v_add_co_u32_e32 v98, vcc, s72, v188
	s_nop 1
	v_addc_co_u32_e32 v99, vcc, 0, v189, vcc
	v_add_co_u32_e32 v102, vcc, s73, v188
	s_nop 1
	v_addc_co_u32_e32 v103, vcc, 0, v189, vcc
	v_add_co_u32_e32 v106, vcc, s33, v190
	global_load_dwordx4 v[98:101], v[98:99], off offset:2176
	s_nop 0
	global_load_dwordx4 v[102:105], v[102:103], off offset:2176
	v_addc_co_u32_e32 v107, vcc, 0, v191, vcc
	v_add_co_u32_e32 v110, vcc, s52, v190
	s_nop 1
	v_addc_co_u32_e32 v111, vcc, 0, v191, vcc
	global_load_dwordx4 v[106:109], v[106:107], off
	s_nop 0
	global_load_dwordx4 v[110:113], v[110:111], off
	ds_read_b64_tr_b16 v[188:189], v198 offset:0
	ds_read_b64_tr_b16 v[190:191], v198 offset:0x800
	ds_read_b64_tr_b16 v[192:193], v198 offset:0x1000
	ds_read_b64_tr_b16 v[194:195], v198 offset:0x1800
	ds_read_b64_tr_b16 v[234:235], v198 offset:0x2000
	ds_read_b64_tr_b16 v[236:237], v198 offset:0x2800
	ds_read_b64_tr_b16 v[238:239], v198 offset:0x3000
	ds_read_b64_tr_b16 v[240:241], v198 offset:0x3800
	ds_read_b64_tr_b16 v[242:243], v198 offset:0x200
	ds_read_b64_tr_b16 v[244:245], v198 offset:0xa00
	s_waitcnt lgkmcnt(8)
; __device__ __forceinline__ void pv_d0(f32x16* o, int vb, bf16x8 pa0, bf16x8 pa1, bf16x8 pa2, bf16x8 pa3) {
;     ...
;   const s16x4 l0 = tr_read<v_rd_off(0, 0, 0)>(vb), h0 = tr_read<v_rd_off(0, 0, 1)>(vb);
;   const s16x4 l1 = tr_read<v_rd_off(0, 1, 0)>(vb), h1 = tr_read<v_rd_off(0, 1, 1)>(vb);
;   const s16x4 l2 = tr_read<v_rd_off(0, 2, 0)>(vb), h2 = tr_read<v_rd_off(0, 2, 1)>(vb);
;   const s16x4 l3 = tr_read<v_rd_off(0, 3, 0)>(vb), h3 = tr_read<v_rd_off(0, 3, 1)>(vb);
;   const s16x4 l4 = tr_read<v_rd_off(1, 0, 0)>(vb), h4 = tr_read<v_rd_off(1, 0, 1)>(vb);
;   asm volatile("s_waitcnt lgkmcnt(8)" ::: "memory"); SBAR();
;   o[0] = __builtin_amdgcn_mfma_f32_32x32x16_bf16(pa0, PK(l0, h0), o[0], 0, 0, 0);
;   const s16x4 l5 = tr_read<v_rd_off(1, 1, 0)>(vb), h5 = tr_read<v_rd_off(1, 1, 1)>(vb);
;   asm volatile("s_waitcnt lgkmcnt(8)" ::: "memory"); SBAR();
;   o[0] = __builtin_amdgcn_mfma_f32_32x32x16_bf16(pa1, PK(l1, h1), o[0], 0, 0, 0);
;   const s16x4 l6 = tr_read<v_rd_off(1, 2, 0)>(vb), h6 = tr_read<v_rd_off(1, 2, 1)>(vb);
;   asm volatile("s_waitcnt lgkmcnt(8)" ::: "memory"); SBAR();
;   o[0] = __builtin_amdgcn_mfma_f32_32x32x16_bf16(pa2, PK(l2, h2), o[0], 0, 0, 0);
;   const s16x4 l7 = tr_read<v_rd_off(1, 3, 0)>(vb), h7 = tr_read<v_rd_off(1, 3, 1)>(vb);
;   asm volatile("s_waitcnt lgkmcnt(8)" ::: "memory"); SBAR();
;   o[0] = __builtin_amdgcn_mfma_f32_32x32x16_bf16(pa3, PK(l3, h3), o[0], 0, 0, 0);
;   const s16x4 l8 = tr_read<v_rd_off(2, 0, 0)>(vb), h8 = tr_read<v_rd_off(2, 0, 1)>(vb);
;   asm volatile("s_waitcnt lgkmcnt(8)" ::: "memory"); SBAR();
;   o[1] = __builtin_amdgcn_mfma_f32_32x32x16_bf16(pa0, PK(l4, h4), o[1], 0, 0, 0);
;   const s16x4 l9 = tr_read<v_rd_off(2, 1, 0)>(vb), h9 = tr_read<v_rd_off(2, 1, 1)>(vb);
;   asm volatile("s_waitcnt lgkmcnt(8)" ::: "memory"); SBAR();
;   o[1] = __builtin_amdgcn_mfma_f32_32x32x16_bf16(pa1, PK(l5, h5), o[1], 0, 0, 0);
;   const s16x4 l10 = tr_read<v_rd_off(2, 2, 0)>(vb), h10 = tr_read<v_rd_off(2, 2, 1)>(vb);
;   asm volatile("s_waitcnt lgkmcnt(8)" ::: "memory"); SBAR();
;   o[1] = __builtin_amdgcn_mfma_f32_32x32x16_bf16(pa2, PK(l6, h6), o[1], 0, 0, 0);
;   const s16x4 l11 = tr_read<v_rd_off(2, 3, 0)>(vb), h11 = tr_read<v_rd_off(2, 3, 1)>(vb);
;   asm volatile("s_waitcnt lgkmcnt(8)" ::: "memory"); SBAR();
;   o[1] = __builtin_amdgcn_mfma_f32_32x32x16_bf16(pa3, PK(l7, h7), o[1], 0, 0, 0);
	s_nop 0
	v_mfma_f32_32x32x16_bf16 v[2:17], v[162:165], v[188:191], v[2:17]
	ds_read_b64_tr_b16 v[188:189], v198 offset:0x1200
	ds_read_b64_tr_b16 v[190:191], v198 offset:0x1a00
	s_waitcnt lgkmcnt(8)
	v_mfma_f32_32x32x16_bf16 v[2:17], v[166:169], v[192:195], v[2:17]
	ds_read_b64_tr_b16 v[192:193], v198 offset:0x2200
	ds_read_b64_tr_b16 v[194:195], v198 offset:0x2a00
	s_waitcnt lgkmcnt(8)
	v_mfma_f32_32x32x16_bf16 v[2:17], v[170:173], v[234:237], v[2:17]
	ds_read_b64_tr_b16 v[234:235], v198 offset:0x3200
	ds_read_b64_tr_b16 v[236:237], v198 offset:0x3a00
	s_waitcnt lgkmcnt(8)
	v_mfma_f32_32x32x16_bf16 v[2:17], v[174:177], v[238:241], v[2:17]
	ds_read_b64_tr_b16 v[238:239], v198 offset:0x400
	ds_read_b64_tr_b16 v[240:241], v198 offset:0xc00
	s_waitcnt lgkmcnt(8)
	v_mfma_f32_32x32x16_bf16 v[50:65], v[162:165], v[242:245], v[50:65]
	ds_read_b64_tr_b16 v[242:243], v198 offset:0x1400
	ds_read_b64_tr_b16 v[244:245], v198 offset:0x1c00
	s_waitcnt lgkmcnt(8)
	v_mfma_f32_32x32x16_bf16 v[50:65], v[166:169], v[188:191], v[50:65]
	ds_read_b64_tr_b16 v[188:189], v198 offset:0x2400
	ds_read_b64_tr_b16 v[190:191], v198 offset:0x2c00
	s_waitcnt lgkmcnt(8)
	v_mfma_f32_32x32x16_bf16 v[50:65], v[170:173], v[192:195], v[50:65]
	ds_read_b64_tr_b16 v[192:193], v198 offset:0x3400
	ds_read_b64_tr_b16 v[194:195], v198 offset:0x3c00
	s_waitcnt lgkmcnt(8)
	v_mfma_f32_32x32x16_bf16 v[50:65], v[174:177], v[234:237], v[50:65]
	ds_read_b64_tr_b16 v[234:235], v198 offset:0x600
	ds_read_b64_tr_b16 v[236:237], v198 offset:0xe00
	s_waitcnt lgkmcnt(8)
	v_mfma_f32_32x32x16_bf16 v[34:49], v[162:165], v[238:241], v[34:49]
	ds_read_b64_tr_b16 v[238:239], v198 offset:0x1600
	ds_read_b64_tr_b16 v[240:241], v198 offset:0x1e00
	s_waitcnt lgkmcnt(8)
	v_mfma_f32_32x32x16_bf16 v[34:49], v[166:169], v[242:245], v[34:49]
	ds_read_b64_tr_b16 v[242:243], v198 offset:0x2600
	ds_read_b64_tr_b16 v[244:245], v198 offset:0x2e00
	s_waitcnt lgkmcnt(8)
	v_mfma_f32_32x32x16_bf16 v[34:49], v[170:173], v[188:191], v[34:49]
	ds_read_b64_tr_b16 v[188:189], v198 offset:0x3600
	ds_read_b64_tr_b16 v[190:191], v198 offset:0x3e00
	s_waitcnt lgkmcnt(8)
	v_mfma_f32_32x32x16_bf16 v[34:49], v[174:177], v[192:195], v[34:49]
	s_waitcnt lgkmcnt(6)
	v_mfma_f32_32x32x16_bf16 v[18:33], v[162:165], v[234:237], v[18:33]
	s_waitcnt lgkmcnt(4)
	v_mfma_f32_32x32x16_bf16 v[18:33], v[166:169], v[238:241], v[18:33]
	s_waitcnt lgkmcnt(2)
	v_mfma_f32_32x32x16_bf16 v[18:33], v[170:173], v[242:245], v[18:33]
	s_waitcnt lgkmcnt(0)
	v_max_f32_e32 v162, v114, v118
	v_max_f32_e32 v163, v115, v119
	v_max_f32_e32 v164, v117, v121
	v_max3_f32 v165, v116, v120, v124
	v_max3_f32 v164, v164, v125, v129
	v_max3_f32 v162, v162, v122, v126
	v_max3_f32 v163, v163, v123, v127
	v_max3_f32 v165, v165, v128, v68
	v_max3_f32 v164, v164, v69, v73
	v_max3_f32 v162, v162, v66, v70
	v_max3_f32 v163, v163, v67, v71
	v_max3_f32 v165, v165, v72, v76
	v_max3_f32 v164, v164, v77, v81
	v_mfma_f32_32x32x16_bf16 v[18:33], v[174:177], v[188:191], v[18:33]
	v_max3_f32 v162, v162, v74, v78
	v_max3_f32 v163, v163, v75, v79
	v_max3_f32 v164, v165, v80, v164
	v_max3_f32 v162, v162, v163, v164
	v_mov_b32_e32 v163, v162
	s_nop 1
	v_permlane32_swap_b32_e32 v162, v163
	v_max_f32_e32 v163, v162, v163
	v_cmp_ge_f32_e32 vcc, s48, v163
	s_cmp_eq_u64 vcc, exec
	v_mov_b32_e32 v162, 1.0
	s_cbranch_scc0 .LBB0_462
	v_mov_b32_e32 v228, v230
